# LRU conv: f32->bf16 RNE bit-trick pair replaced by v_cvt_pk_bf16_f32 (32 fewer VALU per wave per unit)
# speedup vs baseline: 1.0041x; 1.0014x over previous
; #define LAS __attribute__((address_space(3)))
; template <int MODE>
; __device__ __forceinline__ void lru_unit(const Args& a, int l, int b, int ch, LAS unsigned char* lds) {
;     int tid_ = threadIdx.x; asm volatile("" : "+v"(tid_));
;     const int tid = tid_, w = __builtin_amdgcn_readfirstlane(tid >> 6), lane = tid & 63, r32 = lane & 31, h = lane >> 5;
;     const int c = w * 64 + lane, t0 = ch * 32;
;     const bf16* proj = (const bf16*)(a.ws + WS_PROJ);
;     LAS unsigned char* xcb = lds + w * 12800;
;     LAS float* au = (LAS float*)(lds + w * 12800 + 4608);
;     const float* cw = a.in[7] + (size_t)l * 4 * LW;
;     const float cw0 = cw[c], cw1 = cw[LW + c], cw2 = cw[2 * LW + c], cw3 = cw[3 * LW + c], cb = a.in[8][l * LW + c];
;     float prm[2][2][3];
; #pragma unroll
;     for (int d = 0; d < 2; ++d)
; #pragma unroll
;         for (int nt = 0; nt < 2; ++nt) { const int cc = (l * 2 + d) * LW + w * 64 + nt * 32 + r32;
;             prm[d][nt][0] = a.in[10][cc]; prm[d][nt][1] = a.in[12][cc]; prm[d][nt][2] = a.in[13][cc]; }
;     const bf16* xp = proj + (size_t)b * SEQ * DIN + c;
;     float xin[35], gl[32];
;     unsigned short xraw[35], graw[32];
; #pragma unroll
;     for (int i = 0; i < 35; ++i) { const int t = t0 - 2 + i, tc = t < 0 ? 0 : (t >= SEQ ? SEQ - 1 : t); xraw[i] = xp[(size_t)tc * DIN]; }
.LBB0_180:
	s_cmpk_gt_i32 s65, 0xff
	s_mov_b64 s[0:1], -1
	s_barrier
	s_cbranch_scc0 .LBB0_182
	s_add_i32 s0, s65, 0xffffff00
	s_lshr_b32 s40, s0, 7
	s_mul_i32 s88, s40, 0x700000
	s_and_b32 s28, s65, 0x7f
	s_lshl_b32 s29, s28, 5
	s_lshl_b64 s[0:1], s[88:89], 1
	s_add_u32 s38, s24, s0
	s_addc_u32 s39, s25, s1
	s_lshl_b32 s0, s40, 21
	s_lshl_b32 s1, s28, 14
	s_or_b32 s88, s0, s1
	s_min_u32 s41, s29, 0xfdf
	s_lshl_b64 s[0:1], s[88:89], 2
	s_add_u32 s44, s72, s0
	s_addc_u32 s45, s73, s1
	s_add_u32 s46, s50, s0
	s_addc_u32 s47, s51, s1
	s_lshl_b32 s0, s40, 17
	s_lshl_b32 s1, s28, 10
	s_or_b32 s88, s0, s1
	s_lshl_b64 s[0:1], s[88:89], 3
	s_add_u32 s42, s74, s0
	s_addc_u32 s43, s75, s1
	v_mov_b32_e32 v66, v226
	s_add_u32 s40, s50, s0
	s_movk_i32 s59, 0xffc0
	v_readfirstlane_b32 s0, v66
	s_mul_i32 s88, s28, 0x1c000
	s_mov_b32 s4, 0x1c000
	v_mov_b32_e32 v0, s0
	v_bfi_b32 v82, s59, v0, v66
	v_ashrrev_i32_e32 v83, 31, v82
	v_lshl_add_u64 v[36:37], v[82:83], 1, s[38:39]
	v_lshl_add_u64 v[4:5], v[36:37], 0, s[88:89]
	v_mov_b32_e32 v214, 0x1c00
	v_mov_b32_e32 v215, 0
	v_mov_b32_e32 v212, v4
	v_mov_b32_e32 v213, v5
	global_load_ushort v210, v[212:213], off
	global_load_ushort v210, v[212:213], off offset:3584
	v_lshl_add_u64 v[212:213], v[212:213], 0, v[214:215]
	global_load_ushort v210, v[212:213], off
	global_load_ushort v210, v[212:213], off offset:3584
	v_lshl_add_u64 v[212:213], v[212:213], 0, v[214:215]
	global_load_ushort v210, v[212:213], off
	global_load_ushort v210, v[212:213], off offset:3584
	v_lshl_add_u64 v[212:213], v[212:213], 0, v[214:215]
	global_load_ushort v210, v[212:213], off
	global_load_ushort v210, v[212:213], off offset:3584
	v_lshl_add_u64 v[212:213], v[212:213], 0, v[214:215]
	global_load_ushort v210, v[212:213], off
	global_load_ushort v210, v[212:213], off offset:3584
	v_lshl_add_u64 v[212:213], v[212:213], 0, v[214:215]
	global_load_ushort v210, v[212:213], off
	global_load_ushort v210, v[212:213], off offset:3584
	v_lshl_add_u64 v[212:213], v[212:213], 0, v[214:215]
	global_load_ushort v210, v[212:213], off
	global_load_ushort v210, v[212:213], off offset:3584
	v_lshl_add_u64 v[212:213], v[212:213], 0, v[214:215]
	global_load_ushort v210, v[212:213], off
	global_load_ushort v210, v[212:213], off offset:3584
	v_lshl_add_u64 v[212:213], v[212:213], 0, v[214:215]
	global_load_ushort v210, v[212:213], off
	global_load_ushort v210, v[212:213], off offset:3584
	v_lshl_add_u64 v[212:213], v[212:213], 0, v[214:215]
	global_load_ushort v210, v[212:213], off
	global_load_ushort v210, v[212:213], off offset:3584
	v_lshl_add_u64 v[212:213], v[212:213], 0, v[214:215]
	global_load_ushort v210, v[212:213], off
	global_load_ushort v210, v[212:213], off offset:3584
	v_lshl_add_u64 v[212:213], v[212:213], 0, v[214:215]
	global_load_ushort v210, v[212:213], off
	global_load_ushort v210, v[212:213], off offset:3584
	v_lshl_add_u64 v[212:213], v[212:213], 0, v[214:215]
	global_load_ushort v210, v[212:213], off
	global_load_ushort v210, v[212:213], off offset:3584
	v_lshl_add_u64 v[212:213], v[212:213], 0, v[214:215]
	global_load_ushort v210, v[212:213], off
	global_load_ushort v210, v[212:213], off offset:3584
	v_lshl_add_u64 v[212:213], v[212:213], 0, v[214:215]
	global_load_ushort v210, v[212:213], off
	global_load_ushort v210, v[212:213], off offset:3584
	v_lshl_add_u64 v[212:213], v[212:213], 0, v[214:215]
	global_load_ushort v210, v[212:213], off
	global_load_ushort v210, v[212:213], off offset:3584
	v_lshl_add_u64 v[212:213], v[212:213], 0, v[214:215]
	s_mul_i32 s88, s41, 0xe00
	v_lshl_add_u64 v[2:3], v[36:37], 0, s[88:89]
	v_add_co_u32_e32 v2, vcc, s4, v2
	v_readlane_b32 s4, v254, 37
	s_nop 0
	v_addc_co_u32_e32 v3, vcc, 0, v3, vcc
	global_load_ushort v0, v[2:3], off
	v_lshlrev_b64 v[2:3], 2, v[82:83]
	v_readlane_b32 s5, v254, 38
	s_movk_i32 s61, 0x1000
	s_movk_i32 s59, 0x2000
	v_lshl_add_u64 v[24:25], s[4:5], 0, v[2:3]
	v_add_co_u32_e32 v26, vcc, s61, v24
	s_movk_i32 s60, 0x3000
	s_nop 0
	v_addc_co_u32_e32 v27, vcc, 0, v25, vcc
	v_add_co_u32_e32 v30, vcc, s61, v4
	s_addc_u32 s41, s51, s1
	s_nop 0
	v_addc_co_u32_e32 v31, vcc, 0, v5, vcc
	v_add_co_u32_e32 v28, vcc, s59, v4
	s_movk_i32 s1, 0x4000
	s_nop 0
	v_addc_co_u32_e32 v29, vcc, 0, v5, vcc
	v_add_co_u32_e32 v32, vcc, s60, v4
	v_and_b32_e32 v164, 31, v66
	s_nop 0
	v_addc_co_u32_e32 v33, vcc, 0, v5, vcc
	v_add_co_u32_e32 v22, vcc, s1, v4
	s_movk_i32 s1, 0x5000
	s_nop 0
	v_addc_co_u32_e32 v23, vcc, 0, v5, vcc
	v_add_co_u32_e32 v10, vcc, s1, v4
	s_movk_i32 s1, 0x6000
	s_nop 0
	v_addc_co_u32_e32 v11, vcc, 0, v5, vcc
	v_add_co_u32_e32 v20, vcc, s1, v4
	s_movk_i32 s1, 0x7000
	s_nop 0
	v_addc_co_u32_e32 v21, vcc, 0, v5, vcc
	v_add_co_u32_e32 v18, vcc, s1, v4
	s_mov_b32 s1, 0x8000
	s_nop 0
	v_addc_co_u32_e32 v19, vcc, 0, v5, vcc
	v_add_co_u32_e32 v12, vcc, s1, v4
	s_mov_b32 s1, 0x9000
	s_nop 0
	v_addc_co_u32_e32 v13, vcc, 0, v5, vcc
	v_add_co_u32_e32 v14, vcc, s1, v4
	s_mov_b32 s1, 0xa000
	s_nop 0
	v_addc_co_u32_e32 v15, vcc, 0, v5, vcc
	v_add_co_u32_e32 v16, vcc, s1, v4
	s_mov_b32 s1, 0xc000
	s_nop 0
	v_addc_co_u32_e32 v17, vcc, 0, v5, vcc
	v_add_co_u32_e32 v6, vcc, s90, v4
	v_readlane_b32 s4, v254, 39
	s_nop 0
	v_addc_co_u32_e32 v7, vcc, 0, v5, vcc
	v_add_co_u32_e32 v8, vcc, s1, v4
	s_and_b32 s1, s0, 0xffffffc0
	s_nop 0
	v_addc_co_u32_e32 v9, vcc, 0, v5, vcc
	s_cmpk_lg_i32 s28, 0x7f
	s_cselect_b64 vcc, -1, 0
	s_add_i32 s28, s29, -2
	s_max_i32 s38, s28, 0
	s_add_i32 s29, s29, -1
	s_mul_i32 s88, s38, 0xe00
	s_max_i32 s38, s29, 0
	v_lshl_add_u64 v[34:35], v[36:37], 0, s[88:89]
	s_mul_i32 s88, s38, 0xe00
	v_lshl_add_u64 v[36:37], v[36:37], 0, s[88:89]
	global_load_ushort v64, v[36:37], off
	global_load_ushort v67, v[32:33], off offset:2048
	global_load_ushort v85, v[30:31], off offset:3072
	global_load_ushort v65, v[34:35], off
	v_or_b32_e32 v30, s4, v164
	v_add_u32_e32 v30, s1, v30
	v_ashrrev_i32_e32 v31, 31, v30
	v_readlane_b32 s4, v252, 16
	v_lshlrev_b64 v[32:33], 2, v[30:31]
	v_readlane_b32 s14, v252, 26
	v_readlane_b32 s15, v252, 27
	s_waitcnt vmcnt(4)
; #define LAS __attribute__((address_space(3)))
; __device__ __forceinline__ unsigned f2bf(float f) { unsigned u = __builtin_bit_cast(unsigned, f); return (u + 0x7fffu + ((u >> 16) & 1u)) >> 16; }
; template <int MODE>
; __device__ __forceinline__ void lru_unit(const Args& a, int l, int b, int ch, LAS unsigned char* lds) {
;     ...
;     const float* cw = a.in[7] + (size_t)l * 4 * LW;
;     const float cw0 = cw[c], cw1 = cw[LW + c], cw2 = cw[2 * LW + c], cw3 = cw[3 * LW + c], cb = a.in[8][l * LW + c];
;     float prm[2][2][3];
; #pragma unroll
;     for (int d = 0; d < 2; ++d)
; #pragma unroll
;         for (int nt = 0; nt < 2; ++nt) { const int cc = (l * 2 + d) * LW + w * 64 + nt * 32 + r32;
;             prm[d][nt][0] = a.in[10][cc]; prm[d][nt][1] = a.in[12][cc]; prm[d][nt][2] = a.in[13][cc]; }
;     const bf16* xp = proj + (size_t)b * SEQ * DIN + c;
;     float xin[35], gl[32];
;     unsigned short xraw[35], graw[32];
; #pragma unroll
;     for (int i = 0; i < 35; ++i) { const int t = t0 - 2 + i, tc = t < 0 ? 0 : (t >= SEQ ? SEQ - 1 : t); xraw[i] = xp[(size_t)tc * DIN]; }
;     if (MODE == 1) {
; #pragma unroll
;         for (int t = 0; t < 32; ++t) graw[t] = xp[(size_t)(t0 + t) * DIN + LW];
;     }
;     asm volatile("" ::: "memory");
; #pragma unroll
;     for (int i = 0; i < 35; ++i) { const int t = t0 - 2 + i; xin[i] = (t >= 0 && t < SEQ) ? bf2f(xraw[i]) : 0.f; }
;     if (MODE == 1) {
; #pragma unroll
;         for (int t = 0; t < 32; ++t) gl[t] = gelu_tanh(bf2f(graw[t]));
;     }
;     float xcr[32], hf[32];
; #pragma unroll
;     for (int t = 0; t < 32; ++t) { const float xc = cw0 * xin[t] + cw1 * xin[t + 1] + cw2 * xin[t + 2] + cw3 * xin[t + 3] + cb; xcr[t] = xc; hf[t] = 0.f;
;         *(LAS bf16*)(xcb + t * 144 + lane * 2) = (bf16)f2bf(xc); }
; #pragma unroll
;     for (int d = 0; d < 2; ++d)
; #pragma unroll
;         for (int nt = 0; nt < 2; ++nt) { prm[d][nt][0] *= -1.4426950408889634f; prm[d][nt][1] *= -1.4426950408889634f;
;             prm[d][nt][2] = -8.f * 1.4426950408889634f * log1pf(__expf(-prm[d][nt][2])); }
	v_lshlrev_b32_e32 v0, 16, v0
	s_mov_b32 s1, 0xd000
	v_lshl_add_u64 v[68:69], s[14:15], 0, v[32:33]
	global_load_dword v30, v[68:69], off
	global_load_ushort v87, v[4:5], off offset:3584
	v_cndmask_b32_e32 v31, 0, v0, vcc
	v_add_co_u32_e32 v34, vcc, s1, v4
	s_mov_b32 s1, 0xe000
	s_nop 0
	v_addc_co_u32_e32 v35, vcc, 0, v5, vcc
	v_add_co_u32_e32 v36, vcc, s1, v4
	s_mov_b32 s1, 0xf000
	s_nop 0
	v_addc_co_u32_e32 v37, vcc, 0, v5, vcc
	v_add_co_u32_e32 v38, vcc, s1, v4
	s_mov_b32 s1, 0x11000
	s_nop 0
	v_addc_co_u32_e32 v39, vcc, 0, v5, vcc
	v_add_co_u32_e32 v40, vcc, s70, v4
	global_load_dword v84, v[68:69], off offset:128
	global_load_dword v88, v[68:69], off offset:2048
	global_load_dword v86, v[68:69], off offset:2176
	v_addc_co_u32_e32 v41, vcc, 0, v5, vcc
	v_add_co_u32_e32 v42, vcc, s1, v4
	s_mov_b32 s1, 0x12000
	s_nop 0
	v_addc_co_u32_e32 v43, vcc, 0, v5, vcc
	v_add_co_u32_e32 v44, vcc, s1, v4
	s_mov_b32 s1, 0x13000
	s_nop 0
	v_addc_co_u32_e32 v45, vcc, 0, v5, vcc
	v_add_co_u32_e32 v46, vcc, s1, v4
	s_mov_b32 s1, 0x14000
	s_nop 0
	v_addc_co_u32_e32 v47, vcc, 0, v5, vcc
	v_add_co_u32_e32 v48, vcc, s1, v4
	s_mov_b32 s1, 0x15000
	s_nop 0
	v_addc_co_u32_e32 v49, vcc, 0, v5, vcc
	v_add_co_u32_e32 v50, vcc, s1, v4
	s_mov_b32 s1, 0x17000
	s_nop 0
	v_addc_co_u32_e32 v51, vcc, 0, v5, vcc
	v_add_co_u32_e32 v52, vcc, s71, v4
	v_readlane_b32 s6, v252, 18
	s_nop 0
	v_addc_co_u32_e32 v53, vcc, 0, v5, vcc
	v_add_co_u32_e32 v54, vcc, s1, v4
	s_mov_b32 s1, 0x18000
	s_nop 0
	v_addc_co_u32_e32 v55, vcc, 0, v5, vcc
	v_add_co_u32_e32 v56, vcc, s1, v4
	s_mov_b32 s1, 0x19000
	s_nop 0
	v_addc_co_u32_e32 v57, vcc, 0, v5, vcc
	v_add_co_u32_e32 v58, vcc, s1, v4
	s_mov_b32 s1, 0x1b000
	s_nop 0
	v_addc_co_u32_e32 v59, vcc, 0, v5, vcc
	v_add_co_u32_e32 v60, vcc, s1, v4
	s_mov_b32 s1, 0x1a000
	s_nop 0
	v_addc_co_u32_e32 v61, vcc, 0, v5, vcc
	v_add_co_u32_e32 v62, vcc, s1, v4
	s_ashr_i32 s1, s0, 6
	s_mul_i32 s0, s1, 0x3200
	s_add_i32 s0, s0, 0
	v_addc_co_u32_e32 v63, vcc, 0, v5, vcc
	s_waitcnt vmcnt(4)
	v_mul_f32_e32 v30, 0xbfb8aa3b, v30
	v_exp_f32_e32 v30, v30
	s_cmpk_lt_u32 s28, 0x1000
	s_cselect_b64 vcc, -1, 0
	s_cmpk_lt_u32 s29, 0x1000
	v_lshlrev_b32_e32 v0, 16, v65
	v_lshlrev_b32_e32 v64, 16, v64
	s_cselect_b64 s[38:39], -1, 0
	v_cndmask_b32_e64 v65, 0, v64, s[38:39]
	v_cndmask_b32_e32 v64, 0, v0, vcc
	s_mov_b32 s6, 0x3f2aaaab
	v_readlane_b32 s7, v252, 19
	s_mov_b32 s7, 0x3f317218
	v_readlane_b32 s10, v252, 22
	s_mov_b32 s10, 0x7f800000
	v_readlane_b32 s11, v252, 23
	s_waitcnt vmcnt(2)
	v_mul_f32_e32 v68, 0xbfb8aa3b, v84
	v_exp_f32_e32 v84, v68
	s_mov_b32 s11, 0x33800000
	s_lshl_b32 s28, s1, 1
	s_ashr_i32 s29, s28, 31
	s_lshl_b64 s[28:29], s[28:29], 13
	v_readlane_b32 s1, v254, 40
	s_add_u32 s28, s1, s28
	v_add_f32_e32 v216, 1.0, v30
	v_add_f32_e32 v217, -1.0, v216
	v_log_f32_e32 v218, v216
	v_rcp_f32_e32 v219, v217
	v_cmp_eq_f32_e32 vcc, 0, v217
	v_mul_f32_e32 v218, v218, v30
	v_mul_f32_e32 v218, 0x3f317218, v218
	v_mul_f32_e32 v218, v218, v219
	v_cndmask_b32_e32 v126, v218, v30, vcc
	v_readlane_b32 s1, v254, 41
	v_bfe_u32 v165, v66, 5, 1
	s_addc_u32 s29, s1, s29
	s_waitcnt vmcnt(1)
	v_mul_f32_e32 v30, 0xbfb8aa3b, v88
	v_exp_f32_e32 v163, v30
	v_readlane_b32 s14, v254, 43
	v_readlane_b32 s5, v252, 17
	v_readlane_b32 s8, v252, 20
	v_readlane_b32 s9, v252, 21
	v_readlane_b32 s12, v252, 24
	v_readlane_b32 s13, v252, 25
	v_add_f32_e32 v216, 1.0, v84
	v_add_f32_e32 v217, -1.0, v216
	v_log_f32_e32 v218, v216
	v_rcp_f32_e32 v219, v217
	v_cmp_eq_f32_e32 vcc, 0, v217
	v_mul_f32_e32 v218, v218, v84
	v_mul_f32_e32 v218, 0x3f317218, v218
	v_mul_f32_e32 v218, v218, v219
	v_cndmask_b32_e32 v124, v218, v84, vcc
	global_load_ushort v69, v[28:29], off offset:2560
	s_nop 0
	global_load_ushort v4, v[4:5], off
	s_nop 0
	global_load_dword v28, v[24:25], off
	global_load_dword v29, v[24:25], off offset:2048
	s_nop 0
	global_load_dword v24, v[26:27], off
	global_load_dword v25, v[26:27], off offset:2048
	global_load_ushort v22, v[22:23], off offset:1536
	s_nop 0
	global_load_ushort v20, v[20:21], off offset:512
	s_nop 0
	global_load_ushort v21, v[18:19], off
	s_nop 0
	global_load_ushort v18, v[18:19], off offset:3584
	s_nop 0
	global_load_ushort v19, v[12:13], off offset:3072
	global_load_ushort v23, v[14:15], off offset:2560
	s_nop 0
	global_load_ushort v16, v[16:17], off offset:2048
	s_nop 0
	global_load_ushort v17, v[10:11], off offset:1024
	v_lshlrev_b32_e32 v0, 4, v165
	v_lshl_add_u64 v[10:11], s[28:29], 0, v[0:1]
	v_lshlrev_b32_e32 v0, 7, v164
	v_lshl_add_u64 v[90:91], v[10:11], 0, v[0:1]
	v_add_u32_e32 v10, s14, v82
	v_ashrrev_i32_e32 v11, 31, v10
	v_lshl_add_u64 v[10:11], v[10:11], 2, s[4:5]
	global_load_dword v73, v[10:11], off
	v_lshl_add_u64 v[10:11], s[8:9], 0, v[32:33]
	v_lshl_add_u64 v[12:13], s[12:13], 0, v[32:33]
	global_load_dword v128, v[10:11], off
	global_load_dword v125, v[10:11], off offset:128
	global_load_dword v161, v[10:11], off offset:2048
	global_load_dword v159, v[10:11], off offset:2176
	global_load_dword v129, v[12:13], off
	global_load_dword v127, v[12:13], off offset:128
	global_load_dword v162, v[12:13], off offset:2048
	global_load_dword v160, v[12:13], off offset:2176
	global_load_ushort v0, v[6:7], off offset:1536
	global_load_ushort v30, v[8:9], off offset:1024
	global_load_ushort v33, v[34:35], off offset:512
	s_nop 0
	global_load_ushort v34, v[36:37], off
	global_load_ushort v35, v[36:37], off offset:3584
	s_nop 0
	global_load_ushort v36, v[38:39], off offset:3072
	global_load_ushort v37, v[40:41], off offset:2560
	s_nop 0
	global_load_ushort v38, v[42:43], off offset:2048
	global_load_ushort v39, v[44:45], off offset:1536
	global_load_ushort v40, v[46:47], off offset:1024
	global_load_ushort v41, v[48:49], off offset:512
	s_nop 0
	global_load_ushort v42, v[50:51], off
	global_load_ushort v43, v[50:51], off offset:3584
	global_load_ushort v44, v[52:53], off offset:3072
	global_load_ushort v45, v[54:55], off offset:2560
	global_load_ushort v46, v[56:57], off offset:2048
	global_load_ushort v47, v[58:59], off offset:1536
	global_load_ushort v48, v[60:61], off offset:512
	global_load_ushort v49, v[62:63], off offset:1024
	v_lshlrev_b32_e32 v9, 16, v87
	v_lshlrev_b32_e32 v12, 16, v85
	v_and_b32_e32 v84, 63, v66
	v_lshl_add_u32 v32, v84, 1, s0
	v_add_co_u32_e32 v108, vcc, s60, v90
	v_lshl_add_u64 v[122:123], s[44:45], 0, v[2:3]
	s_nop 0
	v_addc_co_u32_e32 v109, vcc, 0, v91, vcc
	s_mov_b32 s1, 0x11f00000
	v_lshlrev_b64 v[82:83], 3, v[82:83]
	v_readlane_b32 s16, v252, 28
	v_readlane_b32 s17, v252, 29
	v_readlane_b32 s18, v252, 30
	v_readlane_b32 s19, v252, 31
	v_readlane_b32 s15, v254, 44
	s_mov_b64 s[8:9], s[26:27]
	s_waitcnt vmcnt(41)
; template <int MODE>
; __device__ __forceinline__ void lru_unit(const Args& a, int l, int b, int ch, LAS unsigned char* lds) {
;     ...
;     for (int i = 0; i < 35; ++i) { const int t = t0 - 2 + i; xin[i] = (t >= 0 && t < SEQ) ? bf2f(xraw[i]) : 0.f; }
;     if (MODE == 1) {
; #pragma unroll
;         for (int t = 0; t < 32; ++t) gl[t] = gelu_tanh(bf2f(graw[t]));
;     }
;     float xcr[32], hf[32];
; #pragma unroll
;     for (int t = 0; t < 32; ++t) { const float xc = cw0 * xin[t] + cw1 * xin[t + 1] + cw2 * xin[t + 2] + cw3 * xin[t + 3] + cb; xcr[t] = xc; hf[t] = 0.f;
	v_lshlrev_b32_e32 v13, 16, v69
	s_waitcnt vmcnt(40)
	v_lshlrev_b32_e32 v8, 16, v4
	s_waitcnt vmcnt(38)
	v_pk_mul_f32 v[6:7], v[28:29], v[64:65]
	s_nop 0
	v_add_f32_e32 v4, v6, v7
	s_waitcnt vmcnt(36)
	v_pk_mul_f32 v[10:11], v[24:25], v[8:9]
	v_pk_mov_b32 v[6:7], v[64:65], v[8:9] op_sel:[1,0]
	v_add_f32_e32 v4, v10, v4
	v_add_f32_e32 v4, v11, v4
	v_pk_mul_f32 v[6:7], v[28:29], v[6:7]
	v_pk_mul_f32 v[10:11], v[28:29], v[8:9]
	v_pk_mov_b32 v[8:9], v[8:9], v[12:13] op_sel:[1,0]
	v_add_f32_e32 v6, v6, v7
	v_pk_mul_f32 v[14:15], v[24:25], v[8:9]
	v_add_f32_e32 v10, v10, v11
	v_add_f32_e32 v6, v6, v14
	v_add_f32_e32 v50, v6, v15
	v_pk_mul_f32 v[6:7], v[24:25], v[12:13]
	s_waitcnt vmcnt(35)
	v_lshlrev_b32_e32 v11, 16, v22
	v_add_f32_e32 v6, v10, v6
	v_lshlrev_b32_e32 v10, 16, v67
	v_add_f32_e32 v51, v6, v7
	v_pk_mul_f32 v[6:7], v[28:29], v[8:9]
	v_pk_mul_f32 v[8:9], v[28:29], v[12:13]
	v_pk_mov_b32 v[12:13], v[12:13], v[10:11] op_sel:[1,0]
	v_add_f32_e32 v6, v6, v7
	v_pk_mul_f32 v[14:15], v[24:25], v[12:13]
	v_add_f32_e32 v8, v8, v9
	v_add_f32_e32 v6, v6, v14
	v_add_f32_e32 v22, v6, v15
	v_pk_mul_f32 v[6:7], v[24:25], v[10:11]
	s_waitcnt vmcnt(27)
	v_add_f32_e32 v85, v73, v4
	v_add_f32_e32 v6, v8, v6
	v_add_f32_e32 v52, v6, v7
	v_pk_mul_f32 v[6:7], v[28:29], v[12:13]
	v_lshlrev_b32_e32 v13, 16, v20
	v_lshlrev_b32_e32 v12, 16, v17
	v_pk_mul_f32 v[8:9], v[28:29], v[10:11]
	v_pk_mov_b32 v[10:11], v[10:11], v[12:13] op_sel:[1,0]
	v_add_f32_e32 v6, v6, v7
	v_pk_mul_f32 v[14:15], v[24:25], v[10:11]
	v_add_f32_e32 v8, v8, v9
	v_add_f32_e32 v6, v6, v14
	v_add_f32_e32 v17, v6, v15
	v_pk_mul_f32 v[6:7], v[24:25], v[12:13]
	v_add_f32_e32 v130, v73, v51
	v_add_f32_e32 v6, v8, v6
	v_add_f32_e32 v20, v6, v7
	v_pk_mul_f32 v[6:7], v[28:29], v[10:11]
	v_lshlrev_b32_e32 v11, 16, v18
	v_lshlrev_b32_e32 v10, 16, v21
	v_pk_mul_f32 v[8:9], v[28:29], v[12:13]
	v_pk_mov_b32 v[12:13], v[12:13], v[10:11] op_sel:[1,0]
	v_add_f32_e32 v6, v6, v7
	v_pk_mul_f32 v[14:15], v[24:25], v[12:13]
	v_add_f32_e32 v8, v8, v9
	v_add_f32_e32 v6, v6, v14
	v_add_f32_e32 v18, v6, v15
	v_pk_mul_f32 v[6:7], v[24:25], v[10:11]
	v_add_f32_e32 v131, v73, v22
	v_add_f32_e32 v6, v8, v6
	v_add_f32_e32 v21, v6, v7
	v_pk_mul_f32 v[6:7], v[28:29], v[12:13]
	v_lshlrev_b32_e32 v13, 16, v23
	v_lshlrev_b32_e32 v12, 16, v19
	v_pk_mul_f32 v[8:9], v[28:29], v[10:11]
	v_pk_mov_b32 v[10:11], v[10:11], v[12:13] op_sel:[1,0]
	v_add_f32_e32 v6, v6, v7
	v_pk_mul_f32 v[14:15], v[24:25], v[10:11]
	v_add_f32_e32 v8, v8, v9
	v_add_f32_e32 v6, v6, v14
	v_add_f32_e32 v19, v6, v15
	v_pk_mul_f32 v[6:7], v[24:25], v[12:13]
	v_add_f32_e32 v132, v73, v52
	v_add_f32_e32 v6, v8, v6
	v_add_f32_e32 v23, v6, v7
	v_pk_mul_f32 v[6:7], v[28:29], v[10:11]
	s_waitcnt vmcnt(18)
	v_lshlrev_b32_e32 v11, 16, v0
	v_lshlrev_b32_e32 v10, 16, v16
	v_pk_mul_f32 v[8:9], v[28:29], v[12:13]
	v_pk_mov_b32 v[12:13], v[12:13], v[10:11] op_sel:[1,0]
	v_add_f32_e32 v0, v6, v7
	v_pk_mul_f32 v[14:15], v[24:25], v[12:13]
	v_pk_mul_f32 v[6:7], v[24:25], v[10:11]
	v_add_f32_e32 v0, v0, v14
	v_add_f32_e32 v16, v0, v15
	v_add_f32_e32 v0, v8, v9
	v_add_f32_e32 v0, v0, v6
	v_add_f32_e32 v53, v0, v7
	v_pk_mul_f32 v[6:7], v[28:29], v[12:13]
	s_waitcnt vmcnt(16)
	v_lshlrev_b32_e32 v13, 16, v33
	v_lshlrev_b32_e32 v12, 16, v30
	v_pk_mul_f32 v[8:9], v[28:29], v[10:11]
	v_pk_mov_b32 v[10:11], v[10:11], v[12:13] op_sel:[1,0]
	v_add_f32_e32 v0, v6, v7
	v_pk_mul_f32 v[14:15], v[24:25], v[10:11]
	v_pk_mul_f32 v[6:7], v[24:25], v[12:13]
	v_add_f32_e32 v0, v0, v14
	v_add_f32_e32 v33, v0, v15
	v_add_f32_e32 v0, v8, v9
	v_add_f32_e32 v0, v0, v6
	v_add_f32_e32 v54, v0, v7
	v_pk_mul_f32 v[6:7], v[28:29], v[10:11]
	s_waitcnt vmcnt(14)
	v_lshlrev_b32_e32 v11, 16, v35
	v_lshlrev_b32_e32 v10, 16, v34
	v_pk_mul_f32 v[8:9], v[28:29], v[12:13]
	v_pk_mov_b32 v[12:13], v[12:13], v[10:11] op_sel:[1,0]
	v_add_f32_e32 v0, v6, v7
	v_pk_mul_f32 v[14:15], v[24:25], v[12:13]
	v_pk_mul_f32 v[6:7], v[24:25], v[10:11]
	v_add_f32_e32 v0, v0, v14
	v_add_f32_e32 v34, v0, v15
	v_add_f32_e32 v0, v8, v9
	v_add_f32_e32 v0, v0, v6
	v_add_f32_e32 v35, v0, v7
	v_pk_mul_f32 v[6:7], v[28:29], v[12:13]
	s_waitcnt vmcnt(12)
	v_lshlrev_b32_e32 v13, 16, v37
	v_lshlrev_b32_e32 v12, 16, v36
	v_pk_mul_f32 v[8:9], v[28:29], v[10:11]
	v_pk_mov_b32 v[10:11], v[10:11], v[12:13] op_sel:[1,0]
	v_add_f32_e32 v0, v6, v7
	v_pk_mul_f32 v[14:15], v[24:25], v[10:11]
	v_pk_mul_f32 v[6:7], v[24:25], v[12:13]
	v_add_f32_e32 v0, v0, v14
	v_add_f32_e32 v36, v0, v15
	v_add_f32_e32 v0, v8, v9
	v_add_f32_e32 v0, v0, v6
	v_add_f32_e32 v37, v0, v7
	v_pk_mul_f32 v[6:7], v[28:29], v[10:11]
	s_waitcnt vmcnt(10)
	v_lshlrev_b32_e32 v11, 16, v39
	v_lshlrev_b32_e32 v10, 16, v38
	v_pk_mul_f32 v[8:9], v[28:29], v[12:13]
	v_pk_mov_b32 v[12:13], v[12:13], v[10:11] op_sel:[1,0]
	v_add_f32_e32 v0, v6, v7
	v_pk_mul_f32 v[14:15], v[24:25], v[12:13]
	v_pk_mul_f32 v[6:7], v[24:25], v[10:11]
	v_add_f32_e32 v0, v0, v14
	v_add_f32_e32 v38, v0, v15
	v_add_f32_e32 v0, v8, v9
	v_add_f32_e32 v0, v0, v6
	v_add_f32_e32 v39, v0, v7
	v_pk_mul_f32 v[6:7], v[28:29], v[12:13]
	s_waitcnt vmcnt(8)
	v_lshlrev_b32_e32 v13, 16, v41
	v_lshlrev_b32_e32 v12, 16, v40
	v_pk_mul_f32 v[8:9], v[28:29], v[10:11]
	v_pk_mov_b32 v[10:11], v[10:11], v[12:13] op_sel:[1,0]
	v_add_f32_e32 v0, v6, v7
	v_pk_mul_f32 v[14:15], v[24:25], v[10:11]
	v_pk_mul_f32 v[6:7], v[24:25], v[12:13]
	v_add_f32_e32 v0, v0, v14
	v_add_f32_e32 v40, v0, v15
	v_add_f32_e32 v0, v8, v9
	v_add_f32_e32 v0, v0, v6
	v_add_f32_e32 v41, v0, v7
	v_pk_mul_f32 v[6:7], v[28:29], v[10:11]
	s_waitcnt vmcnt(6)
; #define LAS __attribute__((address_space(3)))
; __device__ __forceinline__ unsigned f2bf(float f) { unsigned u = __builtin_bit_cast(unsigned, f); return (u + 0x7fffu + ((u >> 16) & 1u)) >> 16; }
; template <int MODE>
; __device__ __forceinline__ void lru_unit(const Args& a, int l, int b, int ch, LAS unsigned char* lds) {
;     ...
;     for (int t = 0; t < 32; ++t) { const float xc = cw0 * xin[t] + cw1 * xin[t + 1] + cw2 * xin[t + 2] + cw3 * xin[t + 3] + cb; xcr[t] = xc; hf[t] = 0.f;
;         *(LAS bf16*)(xcb + t * 144 + lane * 2) = (bf16)f2bf(xc); }
	v_lshlrev_b32_e32 v11, 16, v43
	v_lshlrev_b32_e32 v10, 16, v42
	v_pk_mul_f32 v[8:9], v[28:29], v[12:13]
	v_pk_mov_b32 v[12:13], v[12:13], v[10:11] op_sel:[1,0]
	v_add_f32_e32 v0, v6, v7
	v_pk_mul_f32 v[14:15], v[24:25], v[12:13]
	v_pk_mul_f32 v[6:7], v[24:25], v[10:11]
	v_add_f32_e32 v0, v0, v14
	v_add_f32_e32 v42, v0, v15
	v_add_f32_e32 v0, v8, v9
	v_add_f32_e32 v0, v0, v6
	v_add_f32_e32 v43, v0, v7
	v_pk_mul_f32 v[6:7], v[28:29], v[12:13]
	s_waitcnt vmcnt(4)
	v_lshlrev_b32_e32 v13, 16, v45
	v_lshlrev_b32_e32 v12, 16, v44
	v_pk_mul_f32 v[8:9], v[28:29], v[10:11]
	v_pk_mov_b32 v[10:11], v[10:11], v[12:13] op_sel:[1,0]
	v_add_f32_e32 v0, v6, v7
	v_pk_mul_f32 v[14:15], v[24:25], v[10:11]
	v_pk_mul_f32 v[6:7], v[24:25], v[12:13]
	v_add_f32_e32 v0, v0, v14
	v_add_f32_e32 v44, v0, v15
	v_add_f32_e32 v0, v8, v9
	v_add_f32_e32 v0, v0, v6
	v_add_f32_e32 v45, v0, v7
	v_pk_mul_f32 v[6:7], v[28:29], v[10:11]
	s_waitcnt vmcnt(2)
	v_lshlrev_b32_e32 v11, 16, v47
	v_lshlrev_b32_e32 v10, 16, v46
	v_pk_mul_f32 v[8:9], v[28:29], v[12:13]
	v_pk_mov_b32 v[12:13], v[12:13], v[10:11] op_sel:[1,0]
	v_add_f32_e32 v0, v6, v7
	v_pk_mul_f32 v[14:15], v[24:25], v[12:13]
	v_pk_mul_f32 v[6:7], v[24:25], v[10:11]
	v_add_f32_e32 v0, v0, v14
	v_add_f32_e32 v46, v0, v15
	v_add_f32_e32 v0, v8, v9
	v_add_f32_e32 v0, v0, v6
	v_add_f32_e32 v47, v0, v7
	v_pk_mul_f32 v[6:7], v[28:29], v[12:13]
	s_waitcnt vmcnt(0)
	v_lshlrev_b32_e32 v12, 16, v49
	v_lshlrev_b32_e32 v13, 16, v48
	v_pk_mul_f32 v[8:9], v[28:29], v[10:11]
	v_pk_mov_b32 v[10:11], v[10:11], v[12:13] op_sel:[1,0]
	v_add_f32_e32 v0, v6, v7
	v_pk_mul_f32 v[14:15], v[24:25], v[10:11]
	v_pk_mul_f32 v[6:7], v[24:25], v[12:13]
	v_add_f32_e32 v0, v0, v14
	v_add_f32_e32 v14, v0, v15
	v_add_f32_e32 v0, v8, v9
	v_add_f32_e32 v0, v0, v6
	v_add_f32_e32 v12, v0, v7
	v_pk_mul_f32 v[6:7], v[28:29], v[10:11]
	v_mov_b32_e32 v30, v13
	v_pk_mul_f32 v[8:9], v[24:25], v[30:31]
	v_add_f32_e32 v0, v6, v7
	v_add_f32_e32 v0, v0, v8
	v_add_f32_e32 v0, v0, v9
	v_add_f32_e32 v87, v73, v0
	v_cvt_pk_bf16_f32 v0, v87, v87
	ds_write_b16_d16_hi v32, v0 offset:4464
	v_cvt_pk_bf16_f32 v0, v85, v85
	ds_write_b16_d16_hi v32, v0
	v_add_f32_e32 v0, v73, v50
	v_cvt_pk_bf16_f32 v4, v0, v0
	ds_write_b16_d16_hi v32, v4 offset:144
	v_cvt_pk_bf16_f32 v4, v130, v130
	ds_write_b16_d16_hi v32, v4 offset:288
	v_cvt_pk_bf16_f32 v4, v131, v131
	ds_write_b16_d16_hi v32, v4 offset:432
	v_cvt_pk_bf16_f32 v4, v132, v132
	v_add_f32_e32 v133, v73, v17
	ds_write_b16_d16_hi v32, v4 offset:576
	v_cvt_pk_bf16_f32 v4, v133, v133
	v_add_f32_e32 v134, v73, v20
	ds_write_b16_d16_hi v32, v4 offset:720
	v_cvt_pk_bf16_f32 v4, v134, v134
	v_add_f32_e32 v135, v73, v18
	ds_write_b16_d16_hi v32, v4 offset:864
	v_cvt_pk_bf16_f32 v4, v135, v135
	v_add_f32_e32 v136, v73, v21
	ds_write_b16_d16_hi v32, v4 offset:1008
	v_cvt_pk_bf16_f32 v4, v136, v136
	v_add_f32_e32 v137, v73, v19
	ds_write_b16_d16_hi v32, v4 offset:1152
	v_cvt_pk_bf16_f32 v4, v137, v137
	v_add_f32_e32 v138, v73, v23
	ds_write_b16_d16_hi v32, v4 offset:1296
	v_cvt_pk_bf16_f32 v4, v138, v138
	v_add_f32_e32 v139, v73, v16
	ds_write_b16_d16_hi v32, v4 offset:1440
	v_cvt_pk_bf16_f32 v4, v139, v139
	v_add_f32_e32 v140, v73, v53
	ds_write_b16_d16_hi v32, v4 offset:1584
	v_cvt_pk_bf16_f32 v4, v140, v140
	v_add_f32_e32 v141, v73, v33
	ds_write_b16_d16_hi v32, v4 offset:1728
	v_cvt_pk_bf16_f32 v4, v141, v141
	v_add_f32_e32 v142, v73, v54
	ds_write_b16_d16_hi v32, v4 offset:1872
	v_cvt_pk_bf16_f32 v4, v142, v142
	v_add_f32_e32 v143, v73, v34
	ds_write_b16_d16_hi v32, v4 offset:2016
	v_cvt_pk_bf16_f32 v4, v143, v143
	v_add_f32_e32 v144, v73, v35
	ds_write_b16_d16_hi v32, v4 offset:2160
	v_cvt_pk_bf16_f32 v4, v144, v144
	v_add_f32_e32 v145, v73, v36
	ds_write_b16_d16_hi v32, v4 offset:2304
	v_cvt_pk_bf16_f32 v4, v145, v145
	v_add_f32_e32 v146, v73, v37
	ds_write_b16_d16_hi v32, v4 offset:2448
	v_cvt_pk_bf16_f32 v4, v146, v146
	v_add_f32_e32 v147, v73, v38
	ds_write_b16_d16_hi v32, v4 offset:2592
	v_cvt_pk_bf16_f32 v4, v147, v147
	v_add_f32_e32 v148, v73, v39
	ds_write_b16_d16_hi v32, v4 offset:2736
	v_cvt_pk_bf16_f32 v4, v148, v148
	v_add_f32_e32 v149, v73, v40
	ds_write_b16_d16_hi v32, v4 offset:2880
	v_cvt_pk_bf16_f32 v4, v149, v149
	v_add_f32_e32 v150, v73, v41
	ds_write_b16_d16_hi v32, v4 offset:3024
	v_cvt_pk_bf16_f32 v4, v150, v150
	v_add_f32_e32 v151, v73, v42
	ds_write_b16_d16_hi v32, v4 offset:3168
	v_cvt_pk_bf16_f32 v4, v151, v151
	v_add_f32_e32 v152, v73, v43
	ds_write_b16_d16_hi v32, v4 offset:3312
	v_cvt_pk_bf16_f32 v4, v152, v152
	v_add_f32_e32 v153, v73, v44
	ds_write_b16_d16_hi v32, v4 offset:3456
	v_cvt_pk_bf16_f32 v4, v153, v153
	v_add_f32_e32 v154, v73, v45
	ds_write_b16_d16_hi v32, v4 offset:3600
	v_cvt_pk_bf16_f32 v4, v154, v154
	v_add_f32_e32 v155, v73, v46
	ds_write_b16_d16_hi v32, v4 offset:3744
	v_cvt_pk_bf16_f32 v4, v155, v155
	v_add_f32_e32 v156, v73, v47
	ds_write_b16_d16_hi v32, v4 offset:3888
	v_cvt_pk_bf16_f32 v4, v156, v156
	v_add_f32_e32 v157, v73, v14
	ds_write_b16_d16_hi v32, v4 offset:4032
	v_cvt_pk_bf16_f32 v4, v157, v157
	v_add_f32_e32 v158, v73, v12
	ds_write_b16_d16_hi v32, v4 offset:4176
	v_cvt_pk_bf16_f32 v4, v158, v158
	ds_write_b16_d16_hi v32, v4 offset:4320
	s_waitcnt lgkmcnt(0)
; #define LAS __attribute__((address_space(3)))
; #define MFMA32(a, b, c) __builtin_amdgcn_mfma_f32_32x32x16_bf16((a), (b), (c), 0, 0, 0)
; template <int DIR, int MODE> ...
;     ...
;         const bf16* wr_ = wl + (size_t)((DIR * 8 + w) * 2) * 4096 + (nt * 32 + r32) * 64 + 8 * h;
; #pragma unroll
;         for (int ks = 0; ks < 4; ++ks) {
;             const bf16x8 bR = *(const bf16x8*)(wr_ + 16 * ks), bI = *(const bf16x8*)(wr_ + 4096 + 16 * ks);
;             accR[nt] = MFMA32(af[ks], bR, accR[nt]); accI[nt] = MFMA32(af[ks], bI, accI[nt]); }
;     }
; #pragma unroll
;     for (int nt = 0; nt < 2; ++nt) {
;         const float nba = prm[DIR][nt][0], nbx = prm[DIR][nt][1], k8l = prm[DIR][nt][2];
; #pragma unroll
;         for (int i = 0; i < 16; ++i) {
;             const float d1 = 1.f + __builtin_amdgcn_exp2f(__builtin_fmaf(accR[nt][i], -1.4426950408889634f, nba));
;             const float d2 = 1.f + __builtin_amdgcn_exp2f(__builtin_fmaf(accI[nt][i], -1.4426950408889634f, nbx));
;             const float inv = __builtin_amdgcn_rcpf(d1 * d2), rr = inv * d2, ii = inv * d1;
;             const float av = __builtin_amdgcn_exp2f(k8l * rr);
;             accR[nt][i] = av; accI[nt][i] = __builtin_amdgcn_sqrtf(fmaxf(__builtin_fmaf(-av, av, 1.f), 0.f)) * ii; }
; template <int MODE>
; __device__ __forceinline__ void lru_unit(const Args& a, int l, int b, int ch, LAS unsigned char* lds) {
;     ...
;     for (int ks = 0; ks < 4; ++ks) af[ks] = *(const LAS bf16x8*)(xcb + r32 * 144 + (16 * ks + 8 * h) * 2);
	global_load_dwordx4 v[6:9], v[90:91], off
	global_load_dwordx4 v[10:13], v[108:109], off offset:-4096
	v_add_co_u32_e32 v34, vcc, s59, v90
	s_nop 1
	v_addc_co_u32_e32 v35, vcc, 0, v91, vcc
	global_load_dwordx4 v[14:17], v[90:91], off offset:32
	global_load_dwordx4 v[18:21], v[34:35], off offset:32
	global_load_dwordx4 v[22:25], v[90:91], off offset:64
	global_load_dwordx4 v[26:29], v[34:35], off offset:64
	global_load_dwordx4 v[30:33], v[90:91], off offset:96
	global_load_dwordx4 v[104:107], v[34:35], off offset:96
	v_add_co_u32_e32 v74, vcc, s61, v90
	s_nop 0
	s_nop 0
	v_addc_co_u32_e32 v75, vcc, 0, v91, vcc
	global_load_dwordx4 v[166:169], v[74:75], off
	global_load_dwordx4 v[174:177], v[74:75], off offset:32
	global_load_dwordx4 v[182:185], v[74:75], off offset:64
	v_lshrrev_b32_e32 v5, 1, v66
	v_mul_u32_u24_e32 v4, 0x90, v164
	v_and_b32_e32 v5, 16, v5
	v_add3_u32 v110, s0, v4, v5
	ds_read_b128 v[70:73], v110
	ds_read_b128 v[66:69], v110 offset:32
	global_load_dwordx4 v[170:173], v[74:75], off offset:96
	s_waitcnt vmcnt(11) lgkmcnt(1)
	v_mfma_f32_32x32x16_bf16 v[34:49], v[70:73], v[6:9], 0
	global_load_dwordx4 v[4:7], v[108:109], off
	global_load_dwordx4 v[178:181], v[108:109], off offset:32
	s_waitcnt vmcnt(12)
	v_mfma_f32_32x32x16_bf16 v[50:65], v[70:73], v[10:13], 0
	ds_read_b128 v[74:77], v110 offset:96
	ds_read_b128 v[78:81], v110 offset:64
	s_waitcnt vmcnt(11) lgkmcnt(2)
	v_mfma_f32_32x32x16_bf16 v[34:49], v[66:69], v[14:17], v[34:49]
	v_mul_f32_e32 v97, 0xbfb8aa3b, v128
	global_load_dwordx4 v[186:189], v[108:109], off offset:64
	global_load_dwordx4 v[200:203], v[108:109], off offset:96
	s_waitcnt vmcnt(12)
	v_mfma_f32_32x32x16_bf16 v[50:65], v[66:69], v[18:21], v[50:65]
	v_mul_f32_e32 v99, 0xbfb8aa3b, v129
	v_mul_f32_e32 v93, 0xbfb8aa3b, v127
	v_lshl_add_u64 v[88:89], s[46:47], 0, v[2:3]
	v_mul_f32_e32 v95, 0xbfb8aa3b, v125
	v_add_co_u32_e32 v120, vcc, s1, v88
	s_waitcnt vmcnt(11) lgkmcnt(0)
	v_mfma_f32_32x32x16_bf16 v[34:49], v[78:81], v[22:25], v[34:49]
	v_addc_co_u32_e32 v121, vcc, 0, v89, vcc
	s_mov_b32 s1, 0x11f01000
	v_add_co_u32_e32 v118, vcc, s1, v88
	s_mov_b32 s1, 0x11f02000
	s_nop 0
	v_addc_co_u32_e32 v119, vcc, 0, v89, vcc
	s_waitcnt vmcnt(10)
	v_mfma_f32_32x32x16_bf16 v[50:65], v[78:81], v[26:29], v[50:65]
	v_add_co_u32_e32 v116, vcc, s1, v88
	s_mov_b32 s1, 0x11f03000
	s_nop 0
	v_addc_co_u32_e32 v117, vcc, 0, v89, vcc
	v_add_co_u32_e32 v114, vcc, s1, v88
	s_waitcnt vmcnt(9)
	v_mfma_f32_32x32x16_bf16 v[34:49], v[74:77], v[30:33], v[34:49]
	v_addc_co_u32_e32 v115, vcc, 0, v89, vcc
	s_mov_b32 s1, 0x11f04000
	v_add_co_u32_e32 v112, vcc, s1, v88
	s_mov_b32 s1, 0x11f05000
	s_nop 0
	v_addc_co_u32_e32 v113, vcc, 0, v89, vcc
	s_waitcnt vmcnt(8)
	v_mfma_f32_32x32x16_bf16 v[50:65], v[74:77], v[104:107], v[50:65]
	s_nop 3
	v_fmamk_f32 v34, v34, 0xbfb8aa3b, v97
	v_fmamk_f32 v101, v35, 0xbfb8aa3b, v97
	v_exp_f32_e32 v34, v34
	v_fmamk_f32 v129, v36, 0xbfb8aa3b, v97
	v_fmamk_f32 v38, v38, 0xbfb8aa3b, v97
	v_fmamk_f32 v39, v39, 0xbfb8aa3b, v97
	v_fmamk_f32 v40, v40, 0xbfb8aa3b, v97
	s_nop 0
	v_fmamk_f32 v50, v50, 0xbfb8aa3b, v99
	v_exp_f32_e32 v35, v50
	v_fmamk_f32 v51, v51, 0xbfb8aa3b, v99
	s_waitcnt vmcnt(7)
	v_mfma_f32_32x32x16_bf16 v[18:33], v[70:73], v[166:169], 0
	v_fmamk_f32 v166, v37, 0xbfb8aa3b, v97
	v_add_f32_e64 v34, v34, 1.0
	v_add_f32_e64 v35, v35, 1.0
	v_exp_f32_e32 v37, v51
	v_mul_f32_e32 v36, v34, v35
	v_rcp_f32_e32 v193, v36
	v_exp_f32_e32 v36, v101
	v_mov_b32_e32 v127, v35
	v_fmamk_f32 v41, v41, 0xbfb8aa3b, v97
	v_fmamk_f32 v42, v42, 0xbfb8aa3b, v97
	v_fmamk_f32 v43, v43, 0xbfb8aa3b, v97
	v_fmamk_f32 v44, v44, 0xbfb8aa3b, v97
	v_fmamk_f32 v45, v45, 0xbfb8aa3b, v97
	v_fmamk_f32 v46, v46, 0xbfb8aa3b, v97
	v_fmamk_f32 v167, v47, 0xbfb8aa3b, v97
	v_fmamk_f32 v168, v48, 0xbfb8aa3b, v97
	v_fmac_f32_e32 v97, 0xbfb8aa3b, v49
	v_pk_mul_f32 v[48:49], v[126:127], v[192:193]
	v_pk_add_f32 v[36:37], v[36:37], 1.0 op_sel_hi:[1,0]
	v_mul_f32_e32 v35, v48, v49
	v_exp_f32_e32 v128, v35
	v_mul_f32_e32 v35, v36, v37
	v_rcp_f32_e32 v49, v35
	v_mul_f32_e32 v50, v34, v193
	v_fma_f32 v34, -v128, v128, 1.0 clamp
	v_fmamk_f32 v47, v52, 0xbfb8aa3b, v99
	v_mul_f32_e32 v35, v37, v49
	v_mul_f32_e32 v35, v48, v35
	v_exp_f32_e32 v126, v35
	v_sqrt_f32_e32 v37, v34
	v_exp_f32_e32 v34, v129
	v_exp_f32_e32 v35, v47
	v_fma_f32 v47, -v126, v126, 1.0 clamp
	v_sqrt_f32_e32 v47, v47
	v_pk_add_f32 v[34:35], v[34:35], 1.0 op_sel_hi:[1,0]
	v_fmamk_f32 v52, v53, 0xbfb8aa3b, v99
	v_mul_f32_e32 v51, v34, v35
	v_rcp_f32_e32 v51, v51
	v_mul_f32_e32 v36, v36, v49
	v_mul_f32_e32 v129, v50, v37
	v_mul_f32_e32 v127, v36, v47
	v_exp_f32_e32 v36, v166
	v_exp_f32_e32 v37, v52
	v_mul_f32_e32 v35, v35, v51
	v_mul_f32_e32 v35, v48, v35
	s_waitcnt vmcnt(6)
; #define MFMA32(a, b, c) __builtin_amdgcn_mfma_f32_32x32x16_bf16((a), (b), (c), 0, 0, 0)
; template <int DIR, int MODE> ...
;     ...
;         const bf16* wr_ = wl + (size_t)((DIR * 8 + w) * 2) * 4096 + (nt * 32 + r32) * 64 + 8 * h;
; #pragma unroll
;         for (int ks = 0; ks < 4; ++ks) {
;             const bf16x8 bR = *(const bf16x8*)(wr_ + 16 * ks), bI = *(const bf16x8*)(wr_ + 4096 + 16 * ks);
;             accR[nt] = MFMA32(af[ks], bR, accR[nt]); accI[nt] = MFMA32(af[ks], bI, accI[nt]); }
;     ...
; #pragma unroll
;     for (int nt = 0; nt < 2; ++nt) {
;         const float nba = prm[DIR][nt][0], nbx = prm[DIR][nt][1], k8l = prm[DIR][nt][2];
; #pragma unroll
;         for (int i = 0; i < 16; ++i) {
;             const float d1 = 1.f + __builtin_amdgcn_exp2f(__builtin_fmaf(accR[nt][i], -1.4426950408889634f, nba));
;             const float d2 = 1.f + __builtin_amdgcn_exp2f(__builtin_fmaf(accI[nt][i], -1.4426950408889634f, nbx));
;             const float inv = __builtin_amdgcn_rcpf(d1 * d2), rr = inv * d2, ii = inv * d1;
;             const float av = __builtin_amdgcn_exp2f(k8l * rr);
;             accR[nt][i] = av; accI[nt][i] = __builtin_amdgcn_sqrtf(fmaxf(__builtin_fmaf(-av, av, 1.f), 0.f)) * ii; }
	v_mfma_f32_32x32x16_bf16 v[18:33], v[66:69], v[174:177], v[18:33]
	v_add_f32_e64 v36, v36, 1.0
	v_add_f32_e64 v37, v37, 1.0
	v_fmamk_f32 v176, v62, 0xbfb8aa3b, v99
	v_exp_f32_e32 v62, v35
	v_mul_f32_e32 v35, v36, v37
	v_rcp_f32_e32 v47, v35
	v_fmamk_f32 v53, v54, 0xbfb8aa3b, v99
	v_mul_f32_e32 v49, v34, v51
	v_fma_f32 v34, -v62, v62, 1.0 clamp
	v_mul_f32_e32 v35, v37, v47
	v_mul_f32_e32 v35, v48, v35
	v_exp_f32_e32 v54, v35
	v_sqrt_f32_e32 v37, v34
	v_exp_f32_e32 v34, v38
	v_exp_f32_e32 v35, v53
	v_fma_f32 v38, -v54, v54, 1.0 clamp
	v_sqrt_f32_e32 v38, v38
	v_pk_add_f32 v[34:35], v[34:35], 1.0 op_sel_hi:[1,0]
	v_fmamk_f32 v169, v55, 0xbfb8aa3b, v99
	v_mul_f32_e32 v50, v34, v35
	v_rcp_f32_e32 v51, v50
	v_mul_f32_e32 v36, v36, v47
	v_fmamk_f32 v177, v63, 0xbfb8aa3b, v99
	v_mul_f32_e32 v63, v49, v37
	v_mul_f32_e32 v55, v36, v38
	v_exp_f32_e32 v36, v39
	v_exp_f32_e32 v37, v169
	v_mul_f32_e32 v35, v35, v51
	v_mul_f32_e32 v35, v48, v35
	v_exp_f32_e32 v50, v35
	v_pk_add_f32 v[36:37], v[36:37], 1.0 op_sel_hi:[1,0]
	v_mul_f32_e32 v39, v34, v51
	v_mul_f32_e32 v35, v36, v37
	v_rcp_f32_e32 v38, v35
	v_fma_f32 v34, -v50, v50, 1.0 clamp
	v_fmamk_f32 v56, v56, 0xbfb8aa3b, v99
	v_mul_f32_e32 v35, v37, v38
	v_mul_f32_e32 v35, v48, v35
	v_exp_f32_e32 v52, v35
	v_sqrt_f32_e32 v37, v34
	v_exp_f32_e32 v34, v40
	v_exp_f32_e32 v35, v56
	v_fma_f32 v40, -v52, v52, 1.0 clamp
	v_sqrt_f32_e32 v40, v40
	v_pk_add_f32 v[34:35], v[34:35], 1.0 op_sel_hi:[1,0]
	v_fmamk_f32 v57, v57, 0xbfb8aa3b, v99
	v_mul_f32_e32 v47, v34, v35
	v_rcp_f32_e32 v47, v47
	v_mul_f32_e32 v36, v36, v38
	v_mul_f32_e32 v51, v39, v37
	v_mul_f32_e32 v53, v36, v40
	v_exp_f32_e32 v36, v41
	v_exp_f32_e32 v37, v57
	v_mul_f32_e32 v35, v35, v47
	v_mul_f32_e32 v35, v48, v35
	v_exp_f32_e32 v56, v35
	v_pk_add_f32 v[36:37], v[36:37], 1.0 op_sel_hi:[1,0]
	v_fmamk_f32 v174, v58, 0xbfb8aa3b, v99
	v_mul_f32_e32 v35, v36, v37
	v_rcp_f32_e32 v40, v35
	v_mul_f32_e32 v41, v34, v47
	v_fma_f32 v34, -v56, v56, 1.0 clamp
	v_mul_f32_e32 v35, v37, v40
	v_mul_f32_e32 v35, v48, v35
	v_exp_f32_e32 v58, v35
	v_sqrt_f32_e32 v37, v34
	v_exp_f32_e32 v34, v42
	v_exp_f32_e32 v35, v174
	v_fma_f32 v38, -v58, v58, 1.0 clamp
	v_sqrt_f32_e32 v42, v38
	v_pk_add_f32 v[38:39], v[34:35], 1.0 op_sel_hi:[1,0]
	v_fmamk_f32 v175, v59, 0xbfb8aa3b, v99
	v_mul_f32_e32 v34, v38, v39
	v_rcp_f32_e32 v35, v34
	v_mul_f32_e32 v57, v41, v37
	v_mul_f32_e32 v34, v36, v40
	v_exp_f32_e32 v36, v43
	v_exp_f32_e32 v37, v175
	v_mul_f32_e32 v59, v34, v42
	v_mul_f32_e32 v34, v39, v35
	v_mul_f32_e32 v34, v48, v34
	v_pk_add_f32 v[40:41], v[36:37], 1.0 op_sel_hi:[1,0]
	v_exp_f32_e32 v34, v34
	v_mul_f32_e32 v36, v40, v41
	v_rcp_f32_e32 v37, v36
	v_mul_f32_e32 v35, v38, v35
	v_fma_f32 v36, -v34, v34, 1.0
	v_max_f32_e32 v38, 0, v36
	v_mul_f32_e32 v36, v41, v37
	v_mul_f32_e32 v36, v48, v36
	v_exp_f32_e32 v36, v36
	v_fmamk_f32 v60, v60, 0xbfb8aa3b, v99
	v_sqrt_f32_e32 v41, v38
	v_exp_f32_e32 v38, v44
	v_exp_f32_e32 v39, v60
	v_fma_f32 v42, -v36, v36, 1.0 clamp
	v_sqrt_f32_e32 v44, v42
	v_pk_add_f32 v[42:43], v[38:39], 1.0 op_sel_hi:[1,0]
	v_fmamk_f32 v61, v61, 0xbfb8aa3b, v99
	v_mul_f32_e32 v38, v42, v43
	v_rcp_f32_e32 v39, v38
	v_mul_f32_e32 v35, v35, v41
	v_mul_f32_e32 v37, v40, v37
	v_exp_f32_e32 v40, v45
	v_exp_f32_e32 v41, v61
	v_mul_f32_e32 v38, v43, v39
	v_mul_f32_e32 v37, v37, v44
	v_mul_f32_e32 v38, v48, v38
	v_pk_add_f32 v[44:45], v[40:41], 1.0 op_sel_hi:[1,0]
	v_exp_f32_e32 v38, v38
	v_mul_f32_e32 v40, v44, v45
	v_rcp_f32_e32 v41, v40
	v_mul_f32_e32 v39, v42, v39
	v_fma_f32 v40, -v38, v38, 1.0
	v_max_f32_e32 v42, 0, v40
	v_mul_f32_e32 v40, v45, v41
	v_mul_f32_e32 v40, v48, v40
	v_exp_f32_e32 v40, v40
	v_sqrt_f32_e32 v45, v42
	v_exp_f32_e32 v42, v46
	v_exp_f32_e32 v43, v176
	v_fma_f32 v46, -v40, v40, 1.0 clamp
	s_waitcnt vmcnt(3)
	v_mfma_f32_32x32x16_bf16 v[2:17], v[70:73], v[4:7], 0
	v_sqrt_f32_e32 v49, v46
	v_pk_add_f32 v[46:47], v[42:43], 1.0 op_sel_hi:[1,0]
	v_mul_f32_e32 v39, v39, v45
	v_mul_f32_e32 v42, v46, v47
	v_rcp_f32_e32 v43, v42
	v_mul_f32_e32 v41, v44, v41
	v_exp_f32_e32 v44, v167
	v_exp_f32_e32 v45, v177
	v_mul_f32_e32 v42, v47, v43
	s_waitcnt vmcnt(2)
	v_mfma_f32_32x32x16_bf16 v[2:17], v[66:69], v[178:181], v[2:17]
	v_mul_f32_e32 v42, v48, v42
	v_add_f32_e64 v60, v44, 1.0
	v_add_f32_e64 v61, v45, 1.0
	v_exp_f32_e32 v42, v42
	v_mul_f32_e32 v44, v60, v61
	v_rcp_f32_e32 v45, v44
	v_mul_f32_e32 v43, v46, v43
	v_fma_f32 v44, -v42, v42, 1.0
	v_max_f32_e32 v46, 0, v44
	v_mul_f32_e32 v44, v61, v45
	v_mul_f32_e32 v44, v48, v44
	v_mfma_f32_32x32x16_bf16 v[18:33], v[78:81], v[182:185], v[18:33]
	v_exp_f32_e32 v44, v44
	v_fmamk_f32 v64, v64, 0xbfb8aa3b, v99
	v_mul_f32_e32 v41, v41, v49
	v_sqrt_f32_e32 v49, v46
	v_exp_f32_e32 v46, v168
	v_exp_f32_e32 v47, v64
	v_fma_f32 v61, -v44, v44, 1.0 clamp
	s_waitcnt vmcnt(1)
	v_mfma_f32_32x32x16_bf16 v[2:17], v[78:81], v[186:189], v[2:17]
	v_sqrt_f32_e32 v61, v61
	v_pk_add_f32 v[46:47], v[46:47], 1.0 op_sel_hi:[1,0]
	v_fmac_f32_e32 v99, 0xbfb8aa3b, v65
	v_mul_f32_e32 v64, v46, v47
	v_mul_f32_e32 v45, v60, v45
	v_rcp_f32_e32 v64, v64
	v_mfma_f32_32x32x16_bf16 v[18:33], v[74:77], v[170:173], v[18:33]
	v_mul_f32_e32 v45, v45, v61
	v_exp_f32_e32 v60, v97
	v_exp_f32_e32 v61, v99
	v_mul_f32_e32 v47, v47, v64
	v_mul_f32_e32 v43, v43, v49
	v_mul_f32_e32 v49, v46, v64
	v_pk_add_f32 v[60:61], v[60:61], 1.0 op_sel_hi:[1,0]
	s_waitcnt vmcnt(0)
; #define LAS __attribute__((address_space(3)))
; template <int DIR, int MODE> ...
;     ...
; #pragma unroll
;     for (int nt = 0; nt < 2; ++nt) {
;         const float nba = prm[DIR][nt][0], nbx = prm[DIR][nt][1], k8l = prm[DIR][nt][2];
; #pragma unroll
;         for (int i = 0; i < 16; ++i) {
;             const float d1 = 1.f + __builtin_amdgcn_exp2f(__builtin_fmaf(accR[nt][i], -1.4426950408889634f, nba));
;             const float d2 = 1.f + __builtin_amdgcn_exp2f(__builtin_fmaf(accI[nt][i], -1.4426950408889634f, nbx));
;             const float inv = __builtin_amdgcn_rcpf(d1 * d2), rr = inv * d2, ii = inv * d1;
;             const float av = __builtin_amdgcn_exp2f(k8l * rr);
;             accR[nt][i] = av; accI[nt][i] = __builtin_amdgcn_sqrtf(fmaxf(__builtin_fmaf(-av, av, 1.f), 0.f)) * ii; }
;     }
;     float hc = 0.f, ap = 1.f;
;     if (MODE == 1) hc = ((const float*)(a.ws + WS_CAR))[(size_t)((b * NCH + ch) * 2 + DIR) * LW + c];
; #pragma unroll
;     for (int hh = 0; hh < 2; ++hh) {
;         const int half = DIR == 0 ? hh : 1 - hh;
; #pragma unroll
;         for (int nt = 0; nt < 2; ++nt)
; #pragma unroll
;             for (int i = 0; i < 8; ++i) { const int tt = 8 * (i >> 2) + 4 * h + (i & 3);
;                 f32x2 v; v.x = accR[nt][8 * half + i]; v.y = accI[nt][8 * half + i];
;                 *(LAS f32x2*)(au + (tt * 64 + nt * 32 + r32) * 2) = v; }
	v_mfma_f32_32x32x16_bf16 v[2:17], v[74:77], v[200:203], v[2:17]
	v_mul_f32_e32 v46, v48, v47
	v_mul_f32_e32 v47, v60, v61
	v_rcp_f32_e32 v97, v47
	v_fmamk_f32 v18, v18, 0xbfb8aa3b, v95
	v_exp_f32_e32 v46, v46
	v_exp_f32_e32 v64, v18
	v_mul_f32_e32 v61, v61, v97
	s_nop 4
	v_fmamk_f32 v2, v2, 0xbfb8aa3b, v93
	v_exp_f32_e32 v65, v2
	v_fma_f32 v47, -v46, v46, 1.0 clamp
	v_mul_f32_e32 v48, v48, v61
	v_pk_add_f32 v[64:65], v[64:65], 1.0 op_sel_hi:[1,0]
	v_exp_f32_e32 v48, v48
	v_mul_f32_e32 v18, v64, v65
	v_sqrt_f32_e32 v47, v47
	v_rcp_f32_e32 v193, v18
	v_fma_f32 v2, -v48, v48, 1.0 clamp
	v_mov_b32_e32 v125, v65
	v_mul_f32_e32 v47, v49, v47
	v_mul_f32_e32 v49, v60, v97
	v_pk_mul_f32 v[60:61], v[124:125], v[192:193]
	v_sqrt_f32_e32 v97, v2
	v_mul_f32_e32 v2, v60, v61
	v_exp_f32_e32 v2, v2
	v_fmamk_f32 v18, v19, 0xbfb8aa3b, v95
	v_fmamk_f32 v3, v3, 0xbfb8aa3b, v93
	v_exp_f32_e32 v18, v18
	v_exp_f32_e32 v19, v3
	v_fma_f32 v3, -v2, v2, 1.0 clamp
	v_sqrt_f32_e32 v3, v3
	v_pk_add_f32 v[18:19], v[18:19], 1.0 op_sel_hi:[1,0]
	v_mul_f32_e32 v64, v64, v193
	v_mul_f32_e32 v61, v18, v19
	v_rcp_f32_e32 v61, v61
	v_fmamk_f32 v20, v20, 0xbfb8aa3b, v95
	v_fmamk_f32 v4, v4, 0xbfb8aa3b, v93
	v_mul_f32_e32 v3, v64, v3
	v_exp_f32_e32 v64, v20
	v_exp_f32_e32 v65, v4
	v_mul_f32_e32 v19, v19, v61
	v_mul_f32_e32 v4, v60, v19
	v_mul_f32_e32 v20, v18, v61
	v_exp_f32_e32 v166, v4
	v_pk_add_f32 v[18:19], v[64:65], 1.0 op_sel_hi:[1,0]
	v_fmamk_f32 v5, v5, 0xbfb8aa3b, v93
	v_mul_f32_e32 v4, v18, v19
	v_rcp_f32_e32 v61, v4
	v_fma_f32 v4, -v166, v166, 1.0 clamp
	v_sqrt_f32_e32 v65, v4
	v_mul_f32_e32 v4, v19, v61
	v_mul_f32_e32 v4, v60, v4
	v_exp_f32_e32 v64, v4
	v_fmamk_f32 v4, v21, 0xbfb8aa3b, v95
	v_exp_f32_e32 v4, v4
	v_exp_f32_e32 v5, v5
	v_fma_f32 v19, -v64, v64, 1.0 clamp
	v_sqrt_f32_e32 v19, v19
	v_pk_add_f32 v[4:5], v[4:5], 1.0 op_sel_hi:[1,0]
	v_mul_f32_e32 v49, v49, v97
	v_mul_f32_e32 v21, v4, v5
	v_rcp_f32_e32 v97, v21
	v_mul_f32_e32 v18, v18, v61
	v_mul_f32_e32 v167, v20, v65
	v_mul_f32_e32 v65, v18, v19
	v_fmamk_f32 v18, v22, 0xbfb8aa3b, v95
	v_fmamk_f32 v6, v6, 0xbfb8aa3b, v93
	v_exp_f32_e32 v20, v18
	v_exp_f32_e32 v21, v6
	v_mul_f32_e32 v5, v5, v97
	v_mul_f32_e32 v19, v4, v97
	v_mul_f32_e32 v4, v60, v5
	v_exp_f32_e32 v18, v4
	v_pk_add_f32 v[4:5], v[20:21], 1.0 op_sel_hi:[1,0]
	v_fmamk_f32 v9, v9, 0xbfb8aa3b, v93
	v_mul_f32_e32 v6, v4, v5
	v_rcp_f32_e32 v61, v6
	v_fma_f32 v6, -v18, v18, 1.0 clamp
	v_sqrt_f32_e32 v22, v6
	v_mul_f32_e32 v5, v5, v61
	v_mul_f32_e32 v5, v60, v5
	v_fmamk_f32 v6, v23, 0xbfb8aa3b, v95
	v_exp_f32_e32 v20, v6
	v_exp_f32_e32 v6, v5
	v_fmamk_f32 v5, v7, 0xbfb8aa3b, v93
	v_exp_f32_e32 v21, v5
	v_mul_f32_e32 v19, v19, v22
	v_fma_f32 v5, -v6, v6, 1.0 clamp
	v_pk_add_f32 v[20:21], v[20:21], 1.0 op_sel_hi:[1,0]
	v_sqrt_f32_e32 v5, v5
	v_mul_f32_e32 v7, v20, v21
	v_rcp_f32_e32 v97, v7
	v_fmamk_f32 v7, v24, 0xbfb8aa3b, v95
	v_exp_f32_e32 v22, v7
	v_fmamk_f32 v7, v8, 0xbfb8aa3b, v93
	v_exp_f32_e32 v23, v7
	v_mul_f32_e32 v4, v4, v61
	v_mul_f32_e32 v7, v4, v5
	v_mul_f32_e32 v8, v21, v97
	v_pk_add_f32 v[4:5], v[22:23], 1.0 op_sel_hi:[1,0]
	v_mul_f32_e32 v8, v60, v8
	v_mul_f32_e32 v21, v4, v5
	v_rcp_f32_e32 v21, v21
	v_mul_f32_e32 v24, v20, v97
	v_exp_f32_e32 v8, v8
	v_exp_f32_e32 v23, v9
	v_mul_f32_e32 v5, v5, v21
	v_mul_f32_e32 v5, v60, v5
	v_exp_f32_e32 v20, v5
	v_fma_f32 v5, -v8, v8, 1.0 clamp
	v_sqrt_f32_e32 v5, v5
	v_fma_f32 v22, -v20, v20, 1.0 clamp
	v_sqrt_f32_e32 v61, v22
	v_fmamk_f32 v22, v25, 0xbfb8aa3b, v95
	v_exp_f32_e32 v22, v22
	v_mul_f32_e32 v4, v4, v21
	v_mul_f32_e32 v9, v24, v5
	v_mul_f32_e32 v21, v4, v61
	v_pk_add_f32 v[4:5], v[22:23], 1.0 op_sel_hi:[1,0]
	v_lshlrev_b32_e32 v23, 11, v165
	v_lshlrev_b32_e32 v24, 3, v164
	v_mul_f32_e32 v22, v4, v5
	v_add3_u32 v24, s0, v23, v24
	v_rcp_f32_e32 v22, v22
	v_add_u32_e32 v124, 0x1000, v24
	ds_write2_b64 v124, v[128:129], v[2:3] offset0:64 offset1:96
	v_fmamk_f32 v2, v26, 0xbfb8aa3b, v95
	v_fmamk_f32 v3, v10, 0xbfb8aa3b, v93
	v_exp_f32_e32 v2, v2
	v_exp_f32_e32 v3, v3
	v_mul_f32_e32 v5, v5, v22
	v_mul_f32_e32 v5, v60, v5
	v_exp_f32_e32 v10, v5
	v_mul_f32_e32 v25, v4, v22
	v_pk_add_f32 v[4:5], v[2:3], 1.0 op_sel_hi:[1,0]
	v_fmamk_f32 v13, v13, 0xbfb8aa3b, v93
	v_mul_f32_e32 v2, v4, v5
	v_rcp_f32_e32 v3, v2
	v_fma_f32 v2, -v10, v10, 1.0 clamp
	v_sqrt_f32_e32 v61, v2
	v_mul_f32_e32 v2, v5, v3
	v_fmamk_f32 v5, v27, 0xbfb8aa3b, v95
	v_mul_f32_e32 v2, v60, v2
	v_exp_f32_e32 v22, v5
	v_fmamk_f32 v5, v11, 0xbfb8aa3b, v93
	v_exp_f32_e32 v2, v2
	v_exp_f32_e32 v23, v5
	v_mul_f32_e32 v3, v4, v3
	v_fmamk_f32 v14, v14, 0xbfb8aa3b, v93
	v_fma_f32 v5, -v2, v2, 1.0 clamp
	v_pk_add_f32 v[26:27], v[22:23], 1.0 op_sel_hi:[1,0]
	v_mul_f32_e32 v11, v26, v27
	v_sqrt_f32_e32 v5, v5
	v_rcp_f32_e32 v97, v11
	v_mul_f32_e32 v11, v25, v61
	ds_write2_b64 v124, v[126:127], v[166:167] offset0:128 offset1:160
	v_mul_f32_e32 v3, v3, v5
	v_mul_f32_e32 v4, v27, v97
	v_fmamk_f32 v5, v28, 0xbfb8aa3b, v95
	v_mul_f32_e32 v4, v60, v4
	v_exp_f32_e32 v22, v5
	v_fmamk_f32 v5, v12, 0xbfb8aa3b, v93
	v_exp_f32_e32 v4, v4
	v_exp_f32_e32 v23, v5
	v_exp_f32_e32 v27, v13
	v_add_u32_e32 v126, 0x1800, v24
	v_fma_f32 v5, -v4, v4, 1.0 clamp
	v_pk_add_f32 v[22:23], v[22:23], 1.0 op_sel_hi:[1,0]
	v_mul_f32_e32 v12, v22, v23
	v_sqrt_f32_e32 v5, v5
	v_rcp_f32_e32 v25, v12
	v_mul_f32_e32 v12, v26, v97
	ds_write2_b64 v126, v[54:55], v[18:19] offset1:32
	v_mul_f32_e32 v5, v12, v5
	v_mul_f32_e32 v12, v23, v25
	v_fmamk_f32 v23, v29, 0xbfb8aa3b, v95
	v_exp_f32_e32 v26, v23
	v_mul_f32_e32 v12, v60, v12
	v_exp_f32_e32 v12, v12
	v_mul_f32_e32 v22, v22, v25
	v_pk_add_f32 v[26:27], v[26:27], 1.0 op_sel_hi:[1,0]
	v_exp_f32_e32 v29, v14
	v_mul_f32_e32 v23, v26, v27
	v_fma_f32 v13, -v12, v12, 1.0 clamp
	v_rcp_f32_e32 v28, v23
	v_sqrt_f32_e32 v13, v13
	v_fmamk_f32 v18, v31, 0xbfb8aa3b, v95
	v_mul_f32_e32 v23, v27, v28
	v_mul_f32_e32 v23, v60, v23
	v_mul_f32_e32 v13, v22, v13
	v_mul_f32_e32 v22, v26, v28
	v_exp_f32_e32 v26, v23
	v_fmamk_f32 v23, v30, 0xbfb8aa3b, v95
	v_exp_f32_e32 v28, v23
	v_fmamk_f32 v15, v15, 0xbfb8aa3b, v93
	v_fma_f32 v14, -v26, v26, 1.0 clamp
	v_pk_add_f32 v[28:29], v[28:29], 1.0 op_sel_hi:[1,0]
	v_exp_f32_e32 v18, v18
	v_mul_f32_e32 v23, v28, v29
	v_exp_f32_e32 v19, v15
	v_sqrt_f32_e32 v14, v14
	v_rcp_f32_e32 v23, v23
	v_add_u32_e32 v127, 0x2000, v24
	v_add_u32_e32 v128, 0x2800, v24
	ds_write2_b64 v124, v[62:63], v[64:65] offset0:192 offset1:224
	ds_write2_b64 v127, v[50:51], v[6:7] offset0:64 offset1:96
	ds_write2_b64 v127, v[52:53], v[8:9] offset0:128 offset1:160
	ds_write2_b64 v127, v[56:57], v[20:21] offset0:192 offset1:224
	ds_write2_b64 v128, v[58:59], v[10:11] offset1:32
	v_lshl_add_u32 v125, v84, 3, s0
	v_pk_add_f32 v[18:19], v[18:19], 1.0 op_sel_hi:[1,0]
	s_waitcnt lgkmcnt(0)
; __device__ __forceinline__ unsigned cvt_pk_bf16(float lo, float hi) { unsigned r; asm volatile("v_cvt_pk_bf16_f32 %0, %1, %2" : "=v"(r) : "v"(lo), "v"(hi)); return r; }
; #define LAS __attribute__((address_space(3)))
; #define LDS_WAVE_SYNC() asm volatile("s_waitcnt lgkmcnt(0)" ::: "memory")
; template <int DIR, int MODE> ...
;     ...
; #pragma unroll
;     for (int nt = 0; nt < 2; ++nt) {
;         const float nba = prm[DIR][nt][0], nbx = prm[DIR][nt][1], k8l = prm[DIR][nt][2];
; #pragma unroll
;         for (int i = 0; i < 16; ++i) {
;             const float d1 = 1.f + __builtin_amdgcn_exp2f(__builtin_fmaf(accR[nt][i], -1.4426950408889634f, nba));
;             const float d2 = 1.f + __builtin_amdgcn_exp2f(__builtin_fmaf(accI[nt][i], -1.4426950408889634f, nbx));
;             const float inv = __builtin_amdgcn_rcpf(d1 * d2), rr = inv * d2, ii = inv * d1;
;             const float av = __builtin_amdgcn_exp2f(k8l * rr);
;             accR[nt][i] = av; accI[nt][i] = __builtin_amdgcn_sqrtf(fmaxf(__builtin_fmaf(-av, av, 1.f), 0.f)) * ii; }
;     ...
;         LDS_WAVE_SYNC();
; #pragma unroll
;         for (int s = 0; s < 16; ++s) {
;             const int tt = DIR == 0 ? s : 15 - s, t = half * 16 + tt;
;             const f32x2 v = *(const LAS f32x2*)(au + (tt * 64 + lane) * 2);
;             hc = v.x * hc + v.y * xcr[t];
;             if (MODE == 0) { ap *= v.x;
;                 ((unsigned*)(a.ws + WS_HP))[((size_t)DIR * T + (size_t)b * SEQ + ch * 32 + t) * LW + c] = pg8::cvt_pk_bf16(hc, ap); }
	v_mul_f32_e32 v27, v22, v14
	v_mul_f32_e32 v14, v29, v23
	v_mul_f32_e32 v22, v28, v23
	v_mul_f32_e32 v23, v18, v19
	ds_read_b64 v[8:9], v125 offset:4608
	v_rcp_f32_e32 v23, v23
	v_mov_b32_e32 v84, v1
	v_mul_f32_e32 v14, v60, v14
	v_exp_f32_e32 v14, v14
	v_mul_f32_e32 v7, v18, v23
	s_waitcnt lgkmcnt(0)
	v_mul_f32_e32 v18, v85, v9
	v_mul_f32_e32 v6, v19, v23
	v_pk_fma_f32 v[18:19], v[84:85], v[8:9], v[18:19] op_sel_hi:[1,1,0]
	v_fma_f32 v15, -v14, v14, 1.0 clamp
	v_cvt_pk_bf16_f32 v19, v18, v8
	ds_read_b64 v[20:21], v125 offset:5120
	v_mul_f32_e32 v6, v60, v6
	v_exp_f32_e32 v6, v6
	v_fmamk_f32 v11, v16, 0xbfb8aa3b, v93
	global_store_dword v[122:123], v19, off
	v_mov_b32_e32 v19, v0
	s_waitcnt lgkmcnt(0)
	v_mul_f32_e32 v16, v0, v21
	v_sqrt_f32_e32 v15, v15
	v_pk_fma_f32 v[18:19], v[18:19], v[20:21], v[16:17] op_sel_hi:[1,1,0]
	v_pk_mul_f32 v[8:9], v[8:9], v[20:21]
	v_fma_f32 v10, -v6, v6, 1.0
	v_cvt_pk_bf16_f32 v16, v18, v8
	ds_read_b64 v[20:21], v125 offset:5632
	v_mul_f32_e32 v15, v22, v15
	v_max_f32_e32 v22, 0, v10
	v_fmamk_f32 v10, v32, 0xbfb8aa3b, v95
	v_exp_f32_e32 v10, v10
	v_exp_f32_e32 v11, v11
	global_store_dword v[120:121], v16, off offset:2048
	v_mov_b32_e32 v19, v130
	s_waitcnt lgkmcnt(0)
	v_mul_f32_e32 v16, v130, v21
	v_pk_fma_f32 v[18:19], v[18:19], v[20:21], v[16:17] op_sel_hi:[1,1,0]
	v_pk_mul_f32 v[8:9], v[8:9], v[20:21]
	v_pk_add_f32 v[10:11], v[10:11], 1.0 op_sel_hi:[1,0]
	v_cvt_pk_bf16_f32 v16, v18, v8
	ds_read_b64 v[20:21], v125 offset:6144
	v_mul_f32_e32 v19, v10, v11
	v_rcp_f32_e32 v23, v19
	global_store_dword v[116:117], v16, off offset:-4096
	v_mov_b32_e32 v19, v131
	s_waitcnt lgkmcnt(0)
	v_mul_f32_e32 v16, v131, v21
	v_pk_fma_f32 v[18:19], v[18:19], v[20:21], v[16:17] op_sel_hi:[1,1,0]
	v_pk_mul_f32 v[8:9], v[8:9], v[20:21]
	v_mov_b32_e32 v19, v132
	v_cvt_pk_bf16_f32 v16, v18, v8
	ds_read_b64 v[20:21], v125 offset:6656
	global_store_dword v[118:119], v16, off offset:2048
	v_sqrt_f32_e32 v22, v22
	v_mul_f32_e32 v11, v11, v23
	v_mul_f32_e32 v11, v60, v11
	s_waitcnt lgkmcnt(0)
	v_mul_f32_e32 v16, v132, v21
	v_pk_fma_f32 v[18:19], v[18:19], v[20:21], v[16:17] op_sel_hi:[1,1,0]
	v_pk_mul_f32 v[8:9], v[8:9], v[20:21]
	v_mul_f32_e32 v7, v7, v22
	v_cvt_pk_bf16_f32 v19, v18, v8
	ds_read_b64 v[20:21], v125 offset:7168
	global_store_dword v[116:117], v19, off
	v_mov_b32_e32 v19, v133
	v_exp_f32_e32 v16, v11
	v_fmac_f32_e32 v95, 0xbfb8aa3b, v33
	s_waitcnt lgkmcnt(0)
	v_mul_f32_e32 v22, v133, v21
	v_pk_fma_f32 v[18:19], v[18:19], v[20:21], v[22:23] op_sel_hi:[1,1,0]
	v_pk_mul_f32 v[8:9], v[8:9], v[20:21]
	v_mul_f32_e32 v23, v10, v23
	v_cvt_pk_bf16_f32 v11, v18, v8
	ds_read_b64 v[20:21], v125 offset:7680
	v_mov_b32_e32 v19, v134
	global_store_dword v[116:117], v11, off offset:2048
	v_fmac_f32_e32 v93, 0xbfb8aa3b, v17
	v_add_co_u32_e32 v110, vcc, s1, v88
	s_waitcnt lgkmcnt(0)
	v_mul_f32_e32 v10, v134, v21
	v_pk_fma_f32 v[10:11], v[18:19], v[20:21], v[10:11] op_sel_hi:[1,1,0]
	v_pk_mul_f32 v[8:9], v[8:9], v[20:21]
	v_exp_f32_e32 v20, v95
	v_cvt_pk_bf16_f32 v11, v10, v8
	ds_read_b64 v[18:19], v125 offset:8192
	global_store_dword v[112:113], v11, off offset:-4096
	v_mov_b32_e32 v11, v135
	v_exp_f32_e32 v21, v93
	v_addc_co_u32_e32 v111, vcc, 0, v89, vcc
	s_waitcnt lgkmcnt(0)
	v_mul_f32_e32 v22, v135, v19
	v_pk_fma_f32 v[10:11], v[10:11], v[18:19], v[22:23] op_sel_hi:[1,1,0]
	v_pk_mul_f32 v[8:9], v[8:9], v[18:19]
	v_pk_add_f32 v[20:21], v[20:21], 1.0 op_sel_hi:[1,0]
	v_cvt_pk_bf16_f32 v11, v10, v8
	ds_read_b64 v[18:19], v125 offset:8704
	global_store_dword v[114:115], v11, off offset:2048
	v_mov_b32_e32 v11, v136
	s_mov_b32 s1, 0x11f06000
	v_add_co_u32_e32 v108, vcc, s1, v88
	s_waitcnt lgkmcnt(0)
	v_mul_f32_e32 v22, v136, v19
	v_pk_fma_f32 v[10:11], v[10:11], v[18:19], v[22:23] op_sel_hi:[1,1,0]
	v_pk_mul_f32 v[8:9], v[8:9], v[18:19]
	v_addc_co_u32_e32 v109, vcc, 0, v89, vcc
	v_cvt_pk_bf16_f32 v11, v10, v8
	ds_read_b64 v[18:19], v125 offset:9216
	global_store_dword v[112:113], v11, off
	v_mov_b32_e32 v11, v137
	v_fma_f32 v24, -v16, v16, 1.0
	v_max_f32_e32 v17, 0, v24
	s_waitcnt lgkmcnt(0)
	v_mul_f32_e32 v22, v137, v19
	v_pk_fma_f32 v[10:11], v[10:11], v[18:19], v[22:23] op_sel_hi:[1,1,0]
	v_pk_mul_f32 v[8:9], v[8:9], v[18:19]
	v_mul_f32_e32 v22, v20, v21
	v_cvt_pk_bf16_f32 v11, v10, v8
	ds_read_b64 v[18:19], v125 offset:9728
	v_rcp_f32_e32 v25, v22
	global_store_dword v[112:113], v11, off offset:2048
	v_mov_b32_e32 v11, v138
	s_mov_b32 s1, 0x11f07000
	s_waitcnt lgkmcnt(0)
	v_mul_f32_e32 v22, v138, v19
	v_pk_fma_f32 v[10:11], v[10:11], v[18:19], v[22:23] op_sel_hi:[1,1,0]
	v_pk_mul_f32 v[8:9], v[8:9], v[18:19]
	v_mul_f32_e32 v21, v21, v25
	v_cvt_pk_bf16_f32 v11, v10, v8
	ds_read_b64 v[18:19], v125 offset:10240
	global_store_dword v[108:109], v11, off offset:-4096
	v_mov_b32_e32 v11, v139
	v_mul_f32_e32 v21, v60, v21
	v_add_co_u32_e32 v106, vcc, s1, v88
	s_waitcnt lgkmcnt(0)
	v_mul_f32_e32 v22, v139, v19
	v_pk_fma_f32 v[10:11], v[10:11], v[18:19], v[22:23] op_sel_hi:[1,1,0]
	v_pk_mul_f32 v[8:9], v[8:9], v[18:19]
	v_exp_f32_e32 v22, v21
	v_cvt_pk_bf16_f32 v11, v10, v8
	ds_read_b64 v[18:19], v125 offset:10752
	global_store_dword v[110:111], v11, off offset:2048
	v_mov_b32_e32 v11, v140
	v_fma_f32 v21, -v22, v22, 1.0 clamp
	s_waitcnt lgkmcnt(0)
	v_mul_f32_e32 v24, v140, v19
	v_pk_fma_f32 v[10:11], v[10:11], v[18:19], v[24:25] op_sel_hi:[1,1,0]
	v_pk_mul_f32 v[8:9], v[8:9], v[18:19]
	v_sqrt_f32_e32 v17, v17
	v_cvt_pk_bf16_f32 v11, v10, v8
	ds_read_b64 v[18:19], v125 offset:11264
	global_store_dword v[108:109], v11, off
	v_mov_b32_e32 v11, v141
	v_sqrt_f32_e32 v21, v21
	v_addc_co_u32_e32 v107, vcc, 0, v89, vcc
	s_waitcnt lgkmcnt(0)
; __device__ __forceinline__ unsigned cvt_pk_bf16(float lo, float hi) { unsigned r; asm volatile("v_cvt_pk_bf16_f32 %0, %1, %2" : "=v"(r) : "v"(lo), "v"(hi)); return r; }
; #define LAS __attribute__((address_space(3)))
; #define LDS_WAVE_SYNC() asm volatile("s_waitcnt lgkmcnt(0)" ::: "memory")
; template <int DIR, int MODE> ...
;     ...
; #pragma unroll
;     for (int hh = 0; hh < 2; ++hh) {
;         const int half = DIR == 0 ? hh : 1 - hh;
; #pragma unroll
;         for (int nt = 0; nt < 2; ++nt)
; #pragma unroll
;             for (int i = 0; i < 8; ++i) { const int tt = 8 * (i >> 2) + 4 * h + (i & 3);
;                 f32x2 v; v.x = accR[nt][8 * half + i]; v.y = accI[nt][8 * half + i];
;                 *(LAS f32x2*)(au + (tt * 64 + nt * 32 + r32) * 2) = v; }
;         LDS_WAVE_SYNC();
; #pragma unroll
;         for (int s = 0; s < 16; ++s) {
;             const int tt = DIR == 0 ? s : 15 - s, t = half * 16 + tt;
;             const f32x2 v = *(const LAS f32x2*)(au + (tt * 64 + lane) * 2);
;             hc = v.x * hc + v.y * xcr[t];
;             if (MODE == 0) { ap *= v.x;
;                 ((unsigned*)(a.ws + WS_HP))[((size_t)DIR * T + (size_t)b * SEQ + ch * 32 + t) * LW + c] = pg8::cvt_pk_bf16(hc, ap); }
;             if (MODE == 1) { if (DIR == 0) hf[t] = hc; else hf[t] = gl[t] * (hf[t] + hc); }
;         }
	v_mul_f32_e32 v24, v141, v19
	v_pk_fma_f32 v[10:11], v[10:11], v[18:19], v[24:25] op_sel_hi:[1,1,0]
	v_pk_mul_f32 v[8:9], v[8:9], v[18:19]
	s_mov_b32 s1, 0x11f08000
	v_cvt_pk_bf16_f32 v11, v10, v8
	ds_read_b64 v[18:19], v125 offset:11776
	global_store_dword v[108:109], v11, off offset:2048
	v_mov_b32_e32 v11, v142
	v_add_co_u32_e32 v104, vcc, s1, v88
	s_waitcnt lgkmcnt(0)
	v_mul_f32_e32 v24, v142, v19
	v_pk_fma_f32 v[10:11], v[10:11], v[18:19], v[24:25] op_sel_hi:[1,1,0]
	v_pk_mul_f32 v[8:9], v[8:9], v[18:19]
	v_addc_co_u32_e32 v105, vcc, 0, v89, vcc
	v_cvt_pk_bf16_f32 v11, v10, v8
	ds_read_b64 v[18:19], v125 offset:12288
	v_mul_f32_e32 v20, v20, v25
	v_mul_f32_e32 v17, v23, v17
	v_mul_f32_e32 v23, v20, v21
	global_store_dword v[104:105], v11, off offset:-4096
	v_mov_b32_e32 v11, v143
	s_waitcnt lgkmcnt(0)
	v_mul_f32_e32 v20, v143, v19
	v_pk_fma_f32 v[10:11], v[10:11], v[18:19], v[20:21] op_sel_hi:[1,1,0]
	v_pk_mul_f32 v[8:9], v[8:9], v[18:19]
	v_cvt_pk_bf16_f32 v11, v10, v8
	global_store_dword v[106:107], v11, off offset:2048
	s_waitcnt lgkmcnt(0)
	ds_write2_b64 v124, v[34:35], v[2:3] offset0:64 offset1:96
	ds_write2_b64 v124, v[36:37], v[4:5] offset0:128 offset1:160
	ds_write2_b64 v124, v[38:39], v[12:13] offset0:192 offset1:224
	ds_write2_b64 v126, v[40:41], v[26:27] offset1:32
	ds_write2_b64 v127, v[42:43], v[14:15] offset0:64 offset1:96
	ds_write2_b64 v127, v[44:45], v[6:7] offset0:128 offset1:160
	ds_write2_b64 v127, v[46:47], v[16:17] offset0:192 offset1:224
	ds_write2_b64 v128, v[48:49], v[22:23] offset1:32
	s_waitcnt lgkmcnt(0)
	ds_read_b64 v[2:3], v125 offset:4608
	v_mov_b32_e32 v11, v144
	s_mov_b32 s1, 0x11f0a000
	s_waitcnt lgkmcnt(0)
	v_mul_f32_e32 v6, v144, v3
	v_pk_fma_f32 v[6:7], v[10:11], v[2:3], v[6:7] op_sel_hi:[1,1,0]
	v_pk_mul_f32 v[2:3], v[8:9], v[2:3]
	v_cvt_pk_bf16_f32 v7, v6, v2
	ds_read_b64 v[8:9], v125 offset:5120
	global_store_dword v[104:105], v7, off
	v_mov_b32_e32 v7, v145
	v_add_co_u32_e32 v10, vcc, s1, v88
	s_waitcnt lgkmcnt(0)
	v_mul_f32_e32 v4, v145, v9
	v_pk_fma_f32 v[6:7], v[6:7], v[8:9], v[4:5] op_sel_hi:[1,1,0]
	v_pk_mul_f32 v[2:3], v[2:3], v[8:9]
	v_mov_b32_e32 v7, v146
	v_cvt_pk_bf16_f32 v4, v6, v2
	ds_read_b64 v[8:9], v125 offset:5632
	global_store_dword v[104:105], v4, off offset:2048
	v_addc_co_u32_e32 v11, vcc, 0, v89, vcc
	s_mov_b32 s0, 0x11f09000
	s_waitcnt lgkmcnt(0)
	v_mul_f32_e32 v4, v146, v9
	v_pk_fma_f32 v[6:7], v[6:7], v[8:9], v[4:5] op_sel_hi:[1,1,0]
	v_pk_mul_f32 v[2:3], v[2:3], v[8:9]
	v_mov_b32_e32 v7, v147
	v_cvt_pk_bf16_f32 v4, v6, v2
	ds_read_b64 v[8:9], v125 offset:6144
	global_store_dword v[10:11], v4, off offset:-4096
	v_add_co_u32_e32 v12, vcc, s0, v88
	s_mov_b32 s1, 0x11f0c000
	s_waitcnt lgkmcnt(0)
	v_mul_f32_e32 v4, v147, v9
	v_pk_fma_f32 v[6:7], v[6:7], v[8:9], v[4:5] op_sel_hi:[1,1,0]
	v_pk_mul_f32 v[2:3], v[2:3], v[8:9]
	v_addc_co_u32_e32 v13, vcc, 0, v89, vcc
	v_cvt_pk_bf16_f32 v4, v6, v2
	ds_read_b64 v[8:9], v125 offset:6656
	global_store_dword v[12:13], v4, off offset:2048
	v_mov_b32_e32 v7, v148
	s_mov_b32 s0, 0x11f0b000
	s_waitcnt lgkmcnt(0)
	v_mul_f32_e32 v4, v148, v9
	v_pk_fma_f32 v[6:7], v[6:7], v[8:9], v[4:5] op_sel_hi:[1,1,0]
	v_pk_mul_f32 v[2:3], v[2:3], v[8:9]
	v_cvt_pk_bf16_f32 v4, v6, v2
	ds_read_b64 v[8:9], v125 offset:7168
	global_store_dword v[10:11], v4, off
	v_mov_b32_e32 v7, v149
	s_waitcnt lgkmcnt(0)
	v_mul_f32_e32 v4, v149, v9
	v_pk_fma_f32 v[4:5], v[6:7], v[8:9], v[4:5] op_sel_hi:[1,1,0]
	v_pk_mul_f32 v[2:3], v[2:3], v[8:9]
	s_nop 0
	v_cvt_pk_bf16_f32 v5, v4, v2
	ds_read_b64 v[6:7], v125 offset:7680
	global_store_dword v[10:11], v5, off offset:2048
	v_mov_b32_e32 v5, v150
	s_waitcnt lgkmcnt(0)
	v_mul_f32_e32 v8, v150, v7
	v_pk_fma_f32 v[4:5], v[4:5], v[6:7], v[8:9] op_sel_hi:[1,1,0]
	v_pk_mul_f32 v[2:3], v[2:3], v[6:7]
	v_add_co_u32_e32 v8, vcc, s1, v88
	v_cvt_pk_bf16_f32 v5, v4, v2
	ds_read_b64 v[6:7], v125 offset:8192
	s_nop 0
	v_addc_co_u32_e32 v9, vcc, 0, v89, vcc
	global_store_dword v[8:9], v5, off offset:-4096
	v_mov_b32_e32 v5, v151
	s_waitcnt lgkmcnt(0)
	v_mul_f32_e32 v10, v151, v7
	v_pk_fma_f32 v[4:5], v[4:5], v[6:7], v[10:11] op_sel_hi:[1,1,0]
	v_pk_mul_f32 v[2:3], v[2:3], v[6:7]
	v_add_co_u32_e32 v10, vcc, s0, v88
	v_cvt_pk_bf16_f32 v5, v4, v2
	ds_read_b64 v[6:7], v125 offset:8704
	s_nop 0
	v_addc_co_u32_e32 v11, vcc, 0, v89, vcc
	global_store_dword v[10:11], v5, off offset:2048
	v_mov_b32_e32 v5, v152
	s_waitcnt lgkmcnt(0)
	v_mul_f32_e32 v10, v152, v7
	v_pk_fma_f32 v[4:5], v[4:5], v[6:7], v[10:11] op_sel_hi:[1,1,0]
	v_pk_mul_f32 v[2:3], v[2:3], v[6:7]
	v_cvt_pk_bf16_f32 v5, v4, v2
	ds_read_b64 v[6:7], v125 offset:9216
	global_store_dword v[8:9], v5, off
	v_mov_b32_e32 v5, v153
	s_mov_b32 s1, 0x11f0e000
	s_waitcnt lgkmcnt(0)
	v_mul_f32_e32 v10, v153, v7
	v_pk_fma_f32 v[4:5], v[4:5], v[6:7], v[10:11] op_sel_hi:[1,1,0]
	v_pk_mul_f32 v[2:3], v[2:3], v[6:7]
	s_mov_b32 s0, 0x11f0d000
	v_cvt_pk_bf16_f32 v5, v4, v2
	ds_read_b64 v[6:7], v125 offset:9728
	global_store_dword v[8:9], v5, off offset:2048
	v_mov_b32_e32 v5, v154
	s_waitcnt lgkmcnt(0)
	v_mul_f32_e32 v8, v154, v7
	v_pk_fma_f32 v[4:5], v[4:5], v[6:7], v[8:9] op_sel_hi:[1,1,0]
	v_pk_mul_f32 v[2:3], v[2:3], v[6:7]
	v_add_co_u32_e32 v8, vcc, s1, v88
	v_cvt_pk_bf16_f32 v5, v4, v2
	ds_read_b64 v[6:7], v125 offset:10240
	s_nop 0
	v_addc_co_u32_e32 v9, vcc, 0, v89, vcc
	global_store_dword v[8:9], v5, off offset:-4096
	v_mov_b32_e32 v5, v155
	s_waitcnt lgkmcnt(0)
	v_mul_f32_e32 v10, v155, v7
	v_pk_fma_f32 v[4:5], v[4:5], v[6:7], v[10:11] op_sel_hi:[1,1,0]
	v_pk_mul_f32 v[2:3], v[2:3], v[6:7]
	v_add_co_u32_e32 v10, vcc, s0, v88
	v_cvt_pk_bf16_f32 v5, v4, v2
	ds_read_b64 v[6:7], v125 offset:10752
	s_nop 0
	v_addc_co_u32_e32 v11, vcc, 0, v89, vcc
	global_store_dword v[10:11], v5, off offset:2048
	v_mov_b32_e32 v5, v156
	s_waitcnt lgkmcnt(0)
; #define LAS __attribute__((address_space(3)))
; template <int DIR, int MODE> ...
;     const int r32 = lane & 31, h = lane >> 5, c = w * 64 + lane;
;     f32x16 accR[2], accI[2];
; #pragma unroll
;     for (int nt = 0; nt < 2; ++nt) {
; #pragma unroll
;         for (int i = 0; i < 16; ++i) { accR[nt][i] = 0.f; accI[nt][i] = 0.f; }
;         const bf16* wr_ = wl + (size_t)((DIR * 8 + w) * 2) * 4096 + (nt * 32 + r32) * 64 + 8 * h;
; #pragma unroll
;         for (int ks = 0; ks < 4; ++ks) {
;             const bf16x8 bR = *(const bf16x8*)(wr_ + 16 * ks), bI = *(const bf16x8*)(wr_ + 4096 + 16 * ks);
;             accR[nt] = MFMA32(af[ks], bR, accR[nt]); accI[nt] = MFMA32(af[ks], bI, accI[nt]); }
;     }
; #pragma unroll
;     for (int nt = 0; nt < 2; ++nt) {
;         const float nba = prm[DIR][nt][0], nbx = prm[DIR][nt][1], k8l = prm[DIR][nt][2];
; #pragma unroll
;         for (int i = 0; i < 16; ++i) {
;             const float d1 = 1.f + __builtin_amdgcn_exp2f(__builtin_fmaf(accR[nt][i], -1.4426950408889634f, nba));
;             const float d2 = 1.f + __builtin_amdgcn_exp2f(__builtin_fmaf(accI[nt][i], -1.4426950408889634f, nbx));
;             const float inv = __builtin_amdgcn_rcpf(d1 * d2), rr = inv * d2, ii = inv * d1;
;             const float av = __builtin_amdgcn_exp2f(k8l * rr);
;             accR[nt][i] = av; accI[nt][i] = __builtin_amdgcn_sqrtf(fmaxf(__builtin_fmaf(-av, av, 1.f), 0.f)) * ii; }
;     }
;     float hc = 0.f, ap = 1.f;
;     if (MODE == 1) hc = ((const float*)(a.ws + WS_CAR))[(size_t)((b * NCH + ch) * 2 + DIR) * LW + c];
; #pragma unroll
;     for (int hh = 0; hh < 2; ++hh) {
;         const int half = DIR == 0 ? hh : 1 - hh;
; #pragma unroll
;         for (int nt = 0; nt < 2; ++nt)
; #pragma unroll
;             for (int i = 0; i < 8; ++i) { const int tt = 8 * (i >> 2) + 4 * h + (i & 3);
;                 f32x2 v; v.x = accR[nt][8 * half + i]; v.y = accI[nt][8 * half + i];
;                 *(LAS f32x2*)(au + (tt * 64 + nt * 32 + r32) * 2) = v; }
;         LDS_WAVE_SYNC();
; #pragma unroll
;         for (int s = 0; s < 16; ++s) {
;             const int tt = DIR == 0 ? s : 15 - s, t = half * 16 + tt;
;             const f32x2 v = *(const LAS f32x2*)(au + (tt * 64 + lane) * 2);
;             hc = v.x * hc + v.y * xcr[t];
;             if (MODE == 0) { ap *= v.x;
	v_mul_f32_e32 v10, v156, v7
	v_pk_fma_f32 v[4:5], v[4:5], v[6:7], v[10:11] op_sel_hi:[1,1,0]
	v_pk_mul_f32 v[2:3], v[2:3], v[6:7]
	s_mov_b32 s0, 0x11f0f000
	v_cvt_pk_bf16_f32 v5, v4, v2
	ds_read_b64 v[6:7], v125 offset:11264
	global_store_dword v[8:9], v5, off
	v_mov_b32_e32 v5, v157
	v_lshl_add_u64 v[10:11], s[42:43], 0, v[82:83]
	s_waitcnt lgkmcnt(0)
	v_mul_f32_e32 v12, v157, v7
	v_pk_fma_f32 v[4:5], v[4:5], v[6:7], v[12:13] op_sel_hi:[1,1,0]
	v_pk_mul_f32 v[2:3], v[2:3], v[6:7]
	v_add_co_u32_e32 v12, vcc, s0, v88
	v_cvt_pk_bf16_f32 v5, v4, v2
	ds_read_b64 v[6:7], v125 offset:11776
	global_store_dword v[8:9], v5, off offset:2048
	v_mov_b32_e32 v5, v158
	v_addc_co_u32_e32 v13, vcc, 0, v89, vcc
	s_waitcnt lgkmcnt(0)
	v_mul_f32_e32 v8, v158, v7
	v_pk_fma_f32 v[4:5], v[4:5], v[6:7], v[8:9] op_sel_hi:[1,1,0]
	v_pk_mul_f32 v[2:3], v[2:3], v[6:7]
	s_mov_b32 s0, 0x21000
	v_cvt_pk_bf16_f32 v5, v4, v2
	ds_read_b64 v[6:7], v125 offset:12288
	global_store_dword v[12:13], v5, off
	v_mov_b32_e32 v5, v87
	v_add_co_u32_e32 v98, vcc, s0, v90
	s_waitcnt lgkmcnt(0)
	v_mul_f32_e32 v8, v87, v7
	v_pk_mul_f32 v[2:3], v[2:3], v[6:7]
	v_pk_fma_f32 v[4:5], v[4:5], v[6:7], v[8:9] op_sel_hi:[1,1,0]
	v_addc_co_u32_e32 v99, vcc, 0, v91, vcc
	v_cvt_pk_bf16_f32 v3, v4, v2
	global_store_dword v[12:13], v3, off offset:2048
	v_mov_b32_e32 v3, v4
	s_waitcnt lgkmcnt(0)
	global_store_dwordx2 v[10:11], v[2:3], off
	global_load_dwordx4 v[2:5], v[98:99], off offset:-4096
	v_mul_f32_e32 v6, 0xbfb8aa3b, v86
	s_mov_b32 s0, 0x23000
	v_exp_f32_e32 v84, v6
	v_add_co_u32_e32 v122, vcc, s0, v90
	s_mov_b64 s[0:1], 0x20000
	s_nop 0
	v_addc_co_u32_e32 v123, vcc, 0, v91, vcc
	global_load_dwordx4 v[6:9], v[122:123], off offset:-4096
	global_load_dwordx4 v[106:109], v[98:99], off offset:96
	v_lshl_add_u64 v[26:27], v[90:91], 0, s[0:1]
	s_mov_b32 s0, 0x22000
	v_add_f32_e32 v216, 1.0, v163
	v_add_f32_e32 v217, -1.0, v216
	v_log_f32_e32 v218, v216
	v_rcp_f32_e32 v219, v217
	v_cmp_eq_f32_e32 vcc, 0, v217
	v_mul_f32_e32 v218, v218, v163
	v_mul_f32_e32 v218, 0x3f317218, v218
	v_mul_f32_e32 v218, v218, v219
	v_cndmask_b32_e32 v100, v218, v163, vcc
	v_add_co_u32_e32 v30, vcc, s0, v90
	s_nop 1
	v_addc_co_u32_e32 v31, vcc, 0, v91, vcc
	global_load_dwordx4 v[10:13], v[26:27], off offset:32
	global_load_dwordx4 v[18:21], v[26:27], off offset:64
	global_load_dwordx4 v[14:17], v[30:31], off offset:32
	global_load_dwordx4 v[22:25], v[30:31], off offset:64
	global_load_dwordx4 v[26:29], v[26:27], off offset:96
	global_load_dwordx4 v[30:33], v[30:31], off offset:96
	global_load_dwordx4 v[90:93], v[98:99], off
	global_load_dwordx4 v[94:97], v[122:123], off
	s_waitcnt vmcnt(10)
	v_mfma_f32_32x32x16_bf16 v[34:49], v[70:73], v[2:5], 0
	global_load_dwordx4 v[102:105], v[98:99], off offset:32
	global_load_dwordx4 v[114:117], v[98:99], off offset:64
	global_load_dwordx4 v[110:113], v[122:123], off offset:32
	global_load_dwordx4 v[118:121], v[122:123], off offset:64
	global_load_dwordx4 v[164:167], v[122:123], off offset:96
	s_waitcnt vmcnt(14)
	v_mfma_f32_32x32x16_bf16 v[50:65], v[70:73], v[6:9], 0
	s_waitcnt vmcnt(12)
	v_mfma_f32_32x32x16_bf16 v[34:49], v[66:69], v[10:13], v[34:49]
	s_waitcnt vmcnt(10)
	v_mfma_f32_32x32x16_bf16 v[50:65], v[66:69], v[14:17], v[50:65]
	s_mov_b32 s0, 0x13f0f000
	v_mfma_f32_32x32x16_bf16 v[34:49], v[78:81], v[18:21], v[34:49]
	s_waitcnt vmcnt(9)
	v_mfma_f32_32x32x16_bf16 v[50:65], v[78:81], v[22:25], v[50:65]
	s_nop 0
	s_waitcnt vmcnt(8)
	v_mfma_f32_32x32x16_bf16 v[34:49], v[74:77], v[26:29], v[34:49]
	s_waitcnt vmcnt(7)
	v_mfma_f32_32x32x16_bf16 v[50:65], v[74:77], v[30:33], v[50:65]
	s_waitcnt vmcnt(6)
	v_mfma_f32_32x32x16_bf16 v[2:17], v[70:73], v[90:93], 0
	s_waitcnt vmcnt(5)
	v_mfma_f32_32x32x16_bf16 v[18:33], v[70:73], v[94:97], 0
	v_mul_f32_e32 v86, 0xbfb8aa3b, v159
	s_nop 0
	s_waitcnt vmcnt(4)
	v_mfma_f32_32x32x16_bf16 v[2:17], v[66:69], v[102:105], v[2:17]
	v_add_f32_e32 v216, 1.0, v84
	v_add_f32_e32 v217, -1.0, v216
	v_log_f32_e32 v218, v216
	v_rcp_f32_e32 v219, v217
	v_cmp_eq_f32_e32 vcc, 0, v217
	v_mul_f32_e32 v218, v218, v84
	v_mul_f32_e32 v218, 0x3f317218, v218
	v_mul_f32_e32 v218, v218, v219
	v_cndmask_b32_e32 v98, v218, v84, vcc
	v_mul_f32_e32 v102, 0xbfb8aa3b, v160
	v_add_co_u32_e32 v96, vcc, s0, v88
	s_mov_b32 s0, 0x13f0e000
	s_nop 0
	v_addc_co_u32_e32 v97, vcc, 0, v89, vcc
	s_waitcnt vmcnt(2)
	v_mfma_f32_32x32x16_bf16 v[18:33], v[66:69], v[110:113], v[18:33]
	v_add_co_u32_e32 v94, vcc, s0, v88
	s_mov_b32 s0, 0x13f0d000
	s_nop 0
	v_addc_co_u32_e32 v95, vcc, 0, v89, vcc
	v_add_co_u32_e32 v92, vcc, s0, v88
	v_mfma_f32_32x32x16_bf16 v[2:17], v[78:81], v[114:117], v[2:17]
	s_nop 0
	v_addc_co_u32_e32 v93, vcc, 0, v89, vcc
	s_mov_b32 s0, 0x13f0c000
	v_add_co_u32_e32 v90, vcc, s0, v88
	s_mov_b32 s0, 0x13f0b000
	s_nop 0
	v_addc_co_u32_e32 v91, vcc, 0, v89, vcc
	s_waitcnt vmcnt(1)
	v_mfma_f32_32x32x16_bf16 v[18:33], v[78:81], v[118:121], v[18:33]
	v_mul_f32_e32 v80, 0xbfb8aa3b, v161
	v_mul_f32_e32 v81, 0xbfb8aa3b, v162
	v_fmamk_f32 v34, v34, 0xbfb8aa3b, v80
	v_exp_f32_e32 v78, v34
	v_fmamk_f32 v34, v50, 0xbfb8aa3b, v81
	v_exp_f32_e32 v79, v34
	v_fmamk_f32 v36, v36, 0xbfb8aa3b, v80
	v_exp_f32_e32 v50, v36
	v_fmamk_f32 v36, v52, 0xbfb8aa3b, v81
	v_pk_add_f32 v[78:79], v[78:79], 1.0 op_sel_hi:[1,0]
	v_mfma_f32_32x32x16_bf16 v[2:17], v[74:77], v[106:109], v[2:17]
	v_mul_f32_e32 v34, v78, v79
	v_rcp_f32_e32 v84, v34
	v_fmamk_f32 v34, v35, 0xbfb8aa3b, v80
	v_fmamk_f32 v35, v51, 0xbfb8aa3b, v81
	v_exp_f32_e32 v34, v34
	v_exp_f32_e32 v35, v35
	v_exp_f32_e32 v51, v36
	v_mul_f32_e32 v79, v79, v84
	v_mul_f32_e32 v78, v78, v84
	v_pk_add_f32 v[34:35], v[34:35], 1.0 op_sel_hi:[1,0]
	v_pk_add_f32 v[50:51], v[50:51], 1.0 op_sel_hi:[1,0]
	v_mul_f32_e32 v36, v34, v35
	v_rcp_f32_e32 v36, v36
	v_mul_f32_e32 v52, v50, v51
	v_rcp_f32_e32 v52, v52
	s_waitcnt vmcnt(0)
; #define MFMA32(a, b, c) __builtin_amdgcn_mfma_f32_32x32x16_bf16((a), (b), (c), 0, 0, 0)
; template <int DIR, int MODE> ...
;     ...
;         for (int ks = 0; ks < 4; ++ks) {
;             const bf16x8 bR = *(const bf16x8*)(wr_ + 16 * ks), bI = *(const bf16x8*)(wr_ + 4096 + 16 * ks);
;             accR[nt] = MFMA32(af[ks], bR, accR[nt]); accI[nt] = MFMA32(af[ks], bI, accI[nt]); }
;     }
; #pragma unroll
;     for (int nt = 0; nt < 2; ++nt) {
;         const float nba = prm[DIR][nt][0], nbx = prm[DIR][nt][1], k8l = prm[DIR][nt][2];
; #pragma unroll
;         for (int i = 0; i < 16; ++i) {
;             const float d1 = 1.f + __builtin_amdgcn_exp2f(__builtin_fmaf(accR[nt][i], -1.4426950408889634f, nba));
;             const float d2 = 1.f + __builtin_amdgcn_exp2f(__builtin_fmaf(accI[nt][i], -1.4426950408889634f, nbx));
;             const float inv = __builtin_amdgcn_rcpf(d1 * d2), rr = inv * d2, ii = inv * d1;
;             const float av = __builtin_amdgcn_exp2f(k8l * rr);
;             accR[nt][i] = av; accI[nt][i] = __builtin_amdgcn_sqrtf(fmaxf(__builtin_fmaf(-av, av, 1.f), 0.f)) * ii; }
;     }
	v_mfma_f32_32x32x16_bf16 v[18:33], v[74:77], v[164:167], v[18:33]
	v_mul_f32_e32 v84, v35, v36
	v_mul_f32_e32 v99, v34, v36
	v_fmamk_f32 v34, v37, 0xbfb8aa3b, v80
	v_fmamk_f32 v35, v53, 0xbfb8aa3b, v81
	v_exp_f32_e32 v34, v34
	v_exp_f32_e32 v35, v35
	v_fmamk_f32 v36, v38, 0xbfb8aa3b, v80
	v_fmamk_f32 v37, v54, 0xbfb8aa3b, v81
	v_exp_f32_e32 v36, v36
	v_exp_f32_e32 v37, v37
	v_pk_add_f32 v[34:35], v[34:35], 1.0 op_sel_hi:[1,0]
	v_mul_f32_e32 v51, v51, v52
	v_mul_f32_e32 v38, v34, v35
	v_rcp_f32_e32 v38, v38
	v_pk_add_f32 v[36:37], v[36:37], 1.0 op_sel_hi:[1,0]
	v_mul_f32_e32 v50, v50, v52
	v_mul_f32_e32 v53, v36, v37
	v_rcp_f32_e32 v53, v53
	v_mul_f32_e32 v52, v35, v38
	v_mul_f32_e32 v54, v34, v38
	v_fmamk_f32 v34, v39, 0xbfb8aa3b, v80
	v_fmamk_f32 v35, v55, 0xbfb8aa3b, v81
	v_exp_f32_e32 v34, v34
	v_exp_f32_e32 v35, v35
	v_mul_f32_e32 v103, v37, v53
	v_fmamk_f32 v37, v40, 0xbfb8aa3b, v80
	v_exp_f32_e32 v38, v37
	v_fmamk_f32 v37, v56, 0xbfb8aa3b, v81
	v_pk_add_f32 v[34:35], v[34:35], 1.0 op_sel_hi:[1,0]
	v_exp_f32_e32 v39, v37
	v_mul_f32_e32 v37, v34, v35
	v_rcp_f32_e32 v37, v37
	v_mul_f32_e32 v53, v36, v53
	v_fmamk_f32 v36, v42, 0xbfb8aa3b, v80
	v_exp_f32_e32 v36, v36
	v_mul_f32_e32 v56, v35, v37
	v_mul_f32_e32 v104, v34, v37
	v_fmamk_f32 v34, v41, 0xbfb8aa3b, v80
	v_fmamk_f32 v35, v57, 0xbfb8aa3b, v81
	v_exp_f32_e32 v34, v34
	v_exp_f32_e32 v35, v35
	v_fmamk_f32 v37, v58, 0xbfb8aa3b, v81
	v_exp_f32_e32 v37, v37
	v_pk_add_f32 v[38:39], v[38:39], 1.0 op_sel_hi:[1,0]
	v_fmamk_f32 v44, v44, 0xbfb8aa3b, v80
	v_mul_f32_e32 v40, v38, v39
	v_rcp_f32_e32 v55, v40
	v_pk_add_f32 v[40:41], v[34:35], 1.0 op_sel_hi:[1,0]
	v_pk_add_f32 v[74:75], v[36:37], 1.0 op_sel_hi:[1,0]
	v_mul_f32_e32 v34, v40, v41
	v_rcp_f32_e32 v35, v34
	v_mul_f32_e32 v34, v74, v75
	v_rcp_f32_e32 v193, v34
	v_mov_b32_e32 v101, v75
	v_mul_f32_e32 v105, v39, v55
	v_mul_f32_e32 v57, v40, v35
	v_pk_mul_f32 v[76:77], v[100:101], v[192:193]
	v_mul_f32_e32 v42, v38, v55
	v_mul_f32_e32 v39, v76, v52
	v_exp_f32_e32 v40, v39
	v_mul_f32_e32 v38, v76, v51
	v_exp_f32_e32 v38, v38
	v_mul_f32_e32 v55, v41, v35
	v_fma_f32 v41, -v40, v40, 1.0 clamp
	v_mul_f32_e32 v51, v76, v56
	v_fma_f32 v39, -v38, v38, 1.0 clamp
	v_sqrt_f32_e32 v41, v41
	v_exp_f32_e32 v52, v51
	v_sqrt_f32_e32 v39, v39
	v_mul_f32_e32 v41, v54, v41
	v_fma_f32 v54, -v52, v52, 1.0
	v_max_f32_e32 v56, 0, v54
	v_mul_f32_e32 v54, v76, v105
	v_mul_f32_e32 v39, v50, v39
	v_mul_f32_e32 v50, v76, v103
	v_exp_f32_e32 v54, v54
	v_exp_f32_e32 v50, v50
	v_mul_f32_e32 v55, v76, v55
	v_sqrt_f32_e32 v58, v56
	v_exp_f32_e32 v56, v55
	v_fma_f32 v55, -v54, v54, 1.0 clamp
	v_fma_f32 v51, -v50, v50, 1.0 clamp
	v_sqrt_f32_e32 v55, v55
	v_sqrt_f32_e32 v51, v51
	v_fma_f32 v75, -v56, v56, 1.0 clamp
	v_mul_f32_e32 v55, v42, v55
	v_fmamk_f32 v42, v43, 0xbfb8aa3b, v80
	v_mul_f32_e32 v51, v53, v51
	v_mul_f32_e32 v53, v104, v58
	v_exp_f32_e32 v58, v42
	v_fmamk_f32 v42, v59, 0xbfb8aa3b, v81
	v_mul_f32_e32 v34, v76, v79
	v_sqrt_f32_e32 v75, v75
	v_exp_f32_e32 v59, v42
	v_exp_f32_e32 v34, v34
	v_mul_f32_e32 v42, v76, v77
	v_mul_f32_e32 v35, v76, v84
	v_mul_f32_e32 v57, v57, v75
	v_mul_f32_e32 v43, v74, v193
	v_exp_f32_e32 v42, v42
	v_pk_add_f32 v[74:75], v[58:59], 1.0 op_sel_hi:[1,0]
	v_exp_f32_e32 v36, v35
	v_fma_f32 v35, -v34, v34, 1.0 clamp
	v_mul_f32_e32 v58, v74, v75
	v_rcp_f32_e32 v59, v58
	v_sqrt_f32_e32 v35, v35
	v_fma_f32 v58, -v42, v42, 1.0 clamp
	v_sqrt_f32_e32 v77, v58
	v_mul_f32_e32 v58, v75, v59
	v_mul_f32_e32 v35, v78, v35
	v_mul_f32_e32 v58, v76, v58
	v_exp_f32_e32 v78, v44
	v_fmamk_f32 v44, v60, 0xbfb8aa3b, v81
	v_exp_f32_e32 v58, v58
	v_exp_f32_e32 v79, v44
	v_fmamk_f32 v45, v45, 0xbfb8aa3b, v80
	v_mul_f32_e32 v59, v74, v59
	v_fma_f32 v44, -v58, v58, 1.0 clamp
	v_pk_add_f32 v[78:79], v[78:79], 1.0 op_sel_hi:[1,0]
	v_mul_f32_e32 v60, v78, v79
	v_sqrt_f32_e32 v44, v44
	v_rcp_f32_e32 v75, v60
	v_exp_f32_e32 v60, v45
	v_fmamk_f32 v45, v61, 0xbfb8aa3b, v81
	v_exp_f32_e32 v61, v45
	v_mul_f32_e32 v59, v59, v44
	v_mul_f32_e32 v44, v79, v75
	v_mul_f32_e32 v44, v76, v44
	v_mul_f32_e32 v45, v78, v75
	v_exp_f32_e32 v44, v44
	v_pk_add_f32 v[74:75], v[60:61], 1.0 op_sel_hi:[1,0]
	v_fmamk_f32 v46, v46, 0xbfb8aa3b, v80
	v_mul_f32_e32 v60, v74, v75
	v_rcp_f32_e32 v61, v60
	v_fma_f32 v60, -v44, v44, 1.0 clamp
	v_mul_f32_e32 v43, v43, v77
	v_sqrt_f32_e32 v77, v60
	v_mul_f32_e32 v60, v75, v61
	v_exp_f32_e32 v78, v46
	v_fmamk_f32 v46, v62, 0xbfb8aa3b, v81
	v_mul_f32_e32 v60, v76, v60
	v_exp_f32_e32 v79, v46
	v_exp_f32_e32 v60, v60
	v_fmamk_f32 v47, v47, 0xbfb8aa3b, v80
	v_mul_f32_e32 v61, v74, v61
	v_pk_add_f32 v[78:79], v[78:79], 1.0 op_sel_hi:[1,0]
	v_fma_f32 v46, -v60, v60, 1.0 clamp
	v_mul_f32_e32 v62, v78, v79
	v_rcp_f32_e32 v75, v62
	v_exp_f32_e32 v62, v47
	v_fmamk_f32 v47, v63, 0xbfb8aa3b, v81
	v_sqrt_f32_e32 v46, v46
	v_exp_f32_e32 v63, v47
	v_mul_f32_e32 v47, v78, v75
	v_mul_f32_e32 v45, v45, v77
	v_mul_f32_e32 v61, v61, v46
	v_mul_f32_e32 v46, v79, v75
	v_pk_add_f32 v[62:63], v[62:63], 1.0 op_sel_hi:[1,0]
	v_mul_f32_e32 v46, v76, v46
	v_mul_f32_e32 v74, v62, v63
	v_exp_f32_e32 v46, v46
	v_rcp_f32_e32 v75, v74
	v_fmamk_f32 v48, v48, 0xbfb8aa3b, v80
	v_exp_f32_e32 v78, v48
	v_fma_f32 v74, -v46, v46, 1.0 clamp
	v_mul_f32_e32 v63, v63, v75
	v_mul_f32_e32 v63, v76, v63
	v_sqrt_f32_e32 v77, v74
	v_exp_f32_e32 v74, v63
	v_fmamk_f32 v48, v64, 0xbfb8aa3b, v81
	v_exp_f32_e32 v79, v48
	v_mul_f32_e32 v62, v62, v75
	v_fma_f32 v48, -v74, v74, 1.0 clamp
	v_sqrt_f32_e32 v48, v48
	v_pk_add_f32 v[78:79], v[78:79], 1.0 op_sel_hi:[1,0]
	v_fmac_f32_e32 v80, 0xbfb8aa3b, v49
	v_mul_f32_e32 v63, v78, v79
	v_fmac_f32_e32 v81, 0xbfb8aa3b, v65
	v_rcp_f32_e32 v63, v63
; template <int DIR, int MODE> ...
;     ...
;     for (int nt = 0; nt < 2; ++nt) {
;         const float nba = prm[DIR][nt][0], nbx = prm[DIR][nt][1], k8l = prm[DIR][nt][2];
; #pragma unroll
;         for (int i = 0; i < 16; ++i) {
;             const float d1 = 1.f + __builtin_amdgcn_exp2f(__builtin_fmaf(accR[nt][i], -1.4426950408889634f, nba));
;             const float d2 = 1.f + __builtin_amdgcn_exp2f(__builtin_fmaf(accI[nt][i], -1.4426950408889634f, nbx));
;             const float inv = __builtin_amdgcn_rcpf(d1 * d2), rr = inv * d2, ii = inv * d1;
;             const float av = __builtin_amdgcn_exp2f(k8l * rr);
;             accR[nt][i] = av; accI[nt][i] = __builtin_amdgcn_sqrtf(fmaxf(__builtin_fmaf(-av, av, 1.f), 0.f)) * ii; }
;     }
	v_mul_f32_e32 v75, v62, v48
	v_exp_f32_e32 v48, v80
	v_exp_f32_e32 v49, v81
	v_mul_f32_e32 v62, v79, v63
	v_mul_f32_e32 v62, v76, v62
	v_exp_f32_e32 v62, v62
	v_pk_add_f32 v[48:49], v[48:49], 1.0 op_sel_hi:[1,0]
	v_mul_f32_e32 v63, v78, v63
	v_mul_f32_e32 v64, v48, v49
	v_rcp_f32_e32 v65, v64
	v_fma_f32 v64, -v62, v62, 1.0 clamp
	v_sqrt_f32_e32 v78, v64
	v_mul_f32_e32 v49, v49, v65
	v_mul_f32_e32 v49, v76, v49
	v_exp_f32_e32 v64, v49
	v_fmamk_f32 v2, v2, 0xbfb8aa3b, v86
	v_exp_f32_e32 v76, v2
	v_fmamk_f32 v2, v18, 0xbfb8aa3b, v102
	v_mul_f32_e32 v47, v47, v77
	v_exp_f32_e32 v77, v2
	v_fma_f32 v2, -v64, v64, 1.0 clamp
	v_sqrt_f32_e32 v2, v2
	v_pk_add_f32 v[76:77], v[76:77], 1.0 op_sel_hi:[1,0]
	v_fmamk_f32 v4, v4, 0xbfb8aa3b, v86
	v_mul_f32_e32 v18, v76, v77
	v_rcp_f32_e32 v49, v18
	v_mul_f32_e32 v18, v48, v65
	v_mul_f32_e32 v65, v18, v2
	v_fmamk_f32 v2, v3, 0xbfb8aa3b, v86
	v_fmamk_f32 v3, v19, 0xbfb8aa3b, v102
	v_exp_f32_e32 v2, v2
	v_exp_f32_e32 v3, v3
	v_exp_f32_e32 v18, v4
	v_fmamk_f32 v4, v20, 0xbfb8aa3b, v102
	v_exp_f32_e32 v19, v4
	v_pk_add_f32 v[2:3], v[2:3], 1.0 op_sel_hi:[1,0]
	v_mul_f32_e32 v48, v77, v49
	v_mul_f32_e32 v4, v2, v3
	v_rcp_f32_e32 v4, v4
	v_mul_f32_e32 v49, v76, v49
	v_pk_add_f32 v[18:19], v[18:19], 1.0 op_sel_hi:[1,0]
	v_mul_f32_e32 v63, v63, v78
	v_mul_f32_e32 v76, v3, v4
	v_mul_f32_e32 v77, v2, v4
	v_fmamk_f32 v2, v5, 0xbfb8aa3b, v86
	v_fmamk_f32 v3, v21, 0xbfb8aa3b, v102
	v_exp_f32_e32 v2, v2
	v_exp_f32_e32 v3, v3
	v_fmamk_f32 v4, v6, 0xbfb8aa3b, v86
	v_fmamk_f32 v5, v22, 0xbfb8aa3b, v102
	v_mul_f32_e32 v20, v18, v19
	v_exp_f32_e32 v4, v4
	v_exp_f32_e32 v5, v5
	v_pk_add_f32 v[2:3], v[2:3], 1.0 op_sel_hi:[1,0]
	v_rcp_f32_e32 v20, v20
	v_mul_f32_e32 v6, v2, v3
	v_rcp_f32_e32 v6, v6
	v_pk_add_f32 v[4:5], v[4:5], 1.0 op_sel_hi:[1,0]
	v_mul_f32_e32 v78, v19, v20
	v_mul_f32_e32 v19, v4, v5
	v_rcp_f32_e32 v19, v19
	v_mul_f32_e32 v80, v3, v6
	v_mul_f32_e32 v81, v2, v6
	v_fmamk_f32 v2, v7, 0xbfb8aa3b, v86
	v_fmamk_f32 v3, v23, 0xbfb8aa3b, v102
	v_exp_f32_e32 v2, v2
	v_exp_f32_e32 v3, v3
	v_mul_f32_e32 v84, v5, v19
	v_fmamk_f32 v5, v8, 0xbfb8aa3b, v86
	v_exp_f32_e32 v6, v5
	v_fmamk_f32 v5, v24, 0xbfb8aa3b, v102
	v_pk_add_f32 v[2:3], v[2:3], 1.0 op_sel_hi:[1,0]
	v_exp_f32_e32 v7, v5
	v_mul_f32_e32 v5, v2, v3
	v_rcp_f32_e32 v5, v5
	v_fma_f32 v37, -v36, v36, 1.0 clamp
	v_pk_add_f32 v[6:7], v[6:7], 1.0 op_sel_hi:[1,0]
	v_mul_f32_e32 v8, v6, v7
	v_mul_f32_e32 v101, v3, v5
	v_mul_f32_e32 v103, v2, v5
	v_fmamk_f32 v2, v10, 0xbfb8aa3b, v86
	v_fmamk_f32 v3, v26, 0xbfb8aa3b, v102
	v_rcp_f32_e32 v8, v8
	v_exp_f32_e32 v2, v2
	v_exp_f32_e32 v3, v3
	v_mul_f32_e32 v100, v4, v19
	v_mul_f32_e32 v104, v7, v8
	v_mul_f32_e32 v105, v6, v8
	v_fmamk_f32 v4, v9, 0xbfb8aa3b, v86
	v_pk_add_f32 v[8:9], v[2:3], 1.0 op_sel_hi:[1,0]
	v_sqrt_f32_e32 v37, v37
	v_mul_f32_e32 v2, v8, v9
	v_rcp_f32_e32 v193, v2
	v_fmamk_f32 v2, v25, 0xbfb8aa3b, v102
	v_exp_f32_e32 v4, v4
	v_exp_f32_e32 v5, v2
	v_mul_f32_e32 v37, v99, v37
	v_mov_b32_e32 v99, v9
	v_mul_f32_e32 v79, v18, v20
	v_pk_mul_f32 v[18:19], v[98:99], v[192:193]
	v_pk_add_f32 v[6:7], v[4:5], 1.0 op_sel_hi:[1,0]
	v_mul_f32_e32 v2, v18, v48
	v_exp_f32_e32 v2, v2
	v_mul_f32_e32 v3, v6, v7
	v_rcp_f32_e32 v3, v3
	v_mul_f32_e32 v9, v18, v19
	v_fma_f32 v4, -v2, v2, 1.0 clamp
	v_sqrt_f32_e32 v5, v4
	v_mul_f32_e32 v4, v18, v76
	v_mul_f32_e32 v76, v6, v3
	v_fmamk_f32 v6, v11, 0xbfb8aa3b, v86
	v_exp_f32_e32 v10, v6
	v_fmamk_f32 v6, v27, 0xbfb8aa3b, v102
	v_exp_f32_e32 v11, v6
	v_mul_f32_e32 v48, v7, v3
	v_exp_f32_e32 v20, v9
	v_mul_f32_e32 v8, v8, v193
	v_pk_add_f32 v[10:11], v[10:11], 1.0 op_sel_hi:[1,0]
	v_add_co_u32_e32 v72, vcc, s0, v88
	v_mul_f32_e32 v7, v10, v11
	v_rcp_f32_e32 v7, v7
	v_addc_co_u32_e32 v73, vcc, 0, v89, vcc
	s_mov_b32 s0, 0x13f0a000
	v_mul_f32_e32 v9, v11, v7
	v_mul_f32_e32 v9, v18, v9
	v_exp_f32_e32 v22, v9
	v_fma_f32 v9, -v20, v20, 1.0 clamp
	v_sqrt_f32_e32 v9, v9
	v_fma_f32 v11, -v22, v22, 1.0 clamp
	v_sqrt_f32_e32 v11, v11
	v_mul_f32_e32 v7, v10, v7
	v_mul_f32_e32 v21, v8, v9
	v_add_co_u32_e32 v70, vcc, s0, v88
	v_mul_f32_e32 v23, v7, v11
	v_fmamk_f32 v7, v12, 0xbfb8aa3b, v86
	v_exp_f32_e32 v8, v7
	v_fmamk_f32 v7, v28, 0xbfb8aa3b, v102
	v_exp_f32_e32 v9, v7
	v_fmamk_f32 v7, v13, 0xbfb8aa3b, v86
	v_exp_f32_e32 v10, v7
	v_fmamk_f32 v7, v29, 0xbfb8aa3b, v102
	v_exp_f32_e32 v11, v7
	v_pk_add_f32 v[8:9], v[8:9], 1.0 op_sel_hi:[1,0]
	v_addc_co_u32_e32 v71, vcc, 0, v89, vcc
	v_mul_f32_e32 v7, v8, v9
	v_rcp_f32_e32 v7, v7
	v_pk_add_f32 v[10:11], v[10:11], 1.0 op_sel_hi:[1,0]
	s_mov_b32 s0, 0x13f09000
	v_mul_f32_e32 v12, v10, v11
	v_rcp_f32_e32 v19, v12
	v_mul_f32_e32 v9, v9, v7
	v_mul_f32_e32 v9, v18, v9
	v_exp_f32_e32 v12, v9
	v_mul_f32_e32 v9, v11, v19
	v_mul_f32_e32 v9, v18, v9
	v_exp_f32_e32 v24, v9
	v_fma_f32 v9, -v12, v12, 1.0 clamp
	v_sqrt_f32_e32 v9, v9
	v_fma_f32 v11, -v24, v24, 1.0 clamp
	v_sqrt_f32_e32 v11, v11
	v_mul_f32_e32 v7, v8, v7
	v_mul_f32_e32 v13, v7, v9
	v_mul_f32_e32 v7, v10, v19
	v_mul_f32_e32 v25, v7, v11
	v_fmamk_f32 v7, v14, 0xbfb8aa3b, v86
	v_exp_f32_e32 v8, v7
	v_fmamk_f32 v7, v30, 0xbfb8aa3b, v102
	v_exp_f32_e32 v9, v7
	v_fmamk_f32 v7, v15, 0xbfb8aa3b, v86
	v_exp_f32_e32 v10, v7
	v_fmamk_f32 v7, v31, 0xbfb8aa3b, v102
	v_exp_f32_e32 v11, v7
	v_pk_add_f32 v[8:9], v[8:9], 1.0 op_sel_hi:[1,0]
	v_mul_f32_e32 v6, v18, v78
	v_mul_f32_e32 v7, v8, v9
	v_rcp_f32_e32 v7, v7
	v_pk_add_f32 v[10:11], v[10:11], 1.0 op_sel_hi:[1,0]
	v_add_co_u32_e32 v68, vcc, s0, v88
	v_mul_f32_e32 v14, v10, v11
	v_rcp_f32_e32 v19, v14
	v_mul_f32_e32 v9, v9, v7
	v_mul_f32_e32 v9, v18, v9
	v_exp_f32_e32 v14, v9
	v_mul_f32_e32 v9, v11, v19
	v_mul_f32_e32 v9, v18, v9
	v_exp_f32_e32 v26, v9
; __device__ __forceinline__ unsigned cvt_pk_bf16(float lo, float hi) { unsigned r; asm volatile("v_cvt_pk_bf16_f32 %0, %1, %2" : "=v"(r) : "v"(lo), "v"(hi)); return r; }
; #define LAS __attribute__((address_space(3)))
; #define LDS_WAVE_SYNC() asm volatile("s_waitcnt lgkmcnt(0)" ::: "memory")
; template <int DIR, int MODE> ...
;     ...
;         for (int i = 0; i < 16; ++i) {
;             const float d1 = 1.f + __builtin_amdgcn_exp2f(__builtin_fmaf(accR[nt][i], -1.4426950408889634f, nba));
;             const float d2 = 1.f + __builtin_amdgcn_exp2f(__builtin_fmaf(accI[nt][i], -1.4426950408889634f, nbx));
;             const float inv = __builtin_amdgcn_rcpf(d1 * d2), rr = inv * d2, ii = inv * d1;
;             const float av = __builtin_amdgcn_exp2f(k8l * rr);
;             accR[nt][i] = av; accI[nt][i] = __builtin_amdgcn_sqrtf(fmaxf(__builtin_fmaf(-av, av, 1.f), 0.f)) * ii; }
;     }
;     float hc = 0.f, ap = 1.f;
;     if (MODE == 1) hc = ((const float*)(a.ws + WS_CAR))[(size_t)((b * NCH + ch) * 2 + DIR) * LW + c];
; #pragma unroll
;     for (int hh = 0; hh < 2; ++hh) {
;         const int half = DIR == 0 ? hh : 1 - hh;
; #pragma unroll
;         for (int nt = 0; nt < 2; ++nt)
; #pragma unroll
;             for (int i = 0; i < 8; ++i) { const int tt = 8 * (i >> 2) + 4 * h + (i & 3);
;                 f32x2 v; v.x = accR[nt][8 * half + i]; v.y = accI[nt][8 * half + i];
;                 *(LAS f32x2*)(au + (tt * 64 + nt * 32 + r32) * 2) = v; }
;         LDS_WAVE_SYNC();
; #pragma unroll
;         for (int s = 0; s < 16; ++s) {
;             const int tt = DIR == 0 ? s : 15 - s, t = half * 16 + tt;
;             const f32x2 v = *(const LAS f32x2*)(au + (tt * 64 + lane) * 2);
;             hc = v.x * hc + v.y * xcr[t];
;             if (MODE == 0) { ap *= v.x;
;                 ((unsigned*)(a.ws + WS_HP))[((size_t)DIR * T + (size_t)b * SEQ + ch * 32 + t) * LW + c] = pg8::cvt_pk_bf16(hc, ap); }
	v_fma_f32 v9, -v14, v14, 1.0 clamp
	v_sqrt_f32_e32 v9, v9
	v_fma_f32 v11, -v26, v26, 1.0 clamp
	v_sqrt_f32_e32 v11, v11
	v_mul_f32_e32 v7, v8, v7
	v_mul_f32_e32 v15, v7, v9
	v_mul_f32_e32 v7, v10, v19
	v_mul_f32_e32 v27, v7, v11
	v_fmamk_f32 v7, v16, 0xbfb8aa3b, v86
	v_exp_f32_e32 v8, v7
	v_fmamk_f32 v7, v32, 0xbfb8aa3b, v102
	v_exp_f32_e32 v9, v7
	v_fmac_f32_e32 v86, 0xbfb8aa3b, v17
	v_fmac_f32_e32 v102, 0xbfb8aa3b, v33
	v_exp_f32_e32 v10, v86
	v_exp_f32_e32 v11, v102
	v_pk_add_f32 v[8:9], v[8:9], 1.0 op_sel_hi:[1,0]
	v_mov_b32_e32 v86, v1
	v_mul_f32_e32 v7, v8, v9
	v_rcp_f32_e32 v7, v7
	v_pk_add_f32 v[10:11], v[10:11], 1.0 op_sel_hi:[1,0]
	v_addc_co_u32_e32 v69, vcc, 0, v89, vcc
	v_mul_f32_e32 v16, v10, v11
	v_rcp_f32_e32 v19, v16
	v_mul_f32_e32 v9, v9, v7
	v_mul_f32_e32 v9, v18, v9
	v_exp_f32_e32 v16, v9
	v_mul_f32_e32 v9, v11, v19
	v_mul_f32_e32 v9, v18, v9
	v_exp_f32_e32 v28, v9
	v_fma_f32 v9, -v16, v16, 1.0 clamp
	v_sqrt_f32_e32 v9, v9
	v_fma_f32 v11, -v28, v28, 1.0 clamp
	v_sqrt_f32_e32 v11, v11
	v_mul_f32_e32 v7, v8, v7
	v_mul_f32_e32 v17, v7, v9
	v_mul_f32_e32 v7, v10, v19
	v_mul_f32_e32 v29, v7, v11
	ds_write2_b64 v124, v[42:43], v[20:21] offset0:64 offset1:96
	ds_write2_b64 v124, v[58:59], v[22:23] offset0:128 offset1:160
	ds_write2_b64 v124, v[44:45], v[12:13] offset0:192 offset1:224
	ds_write2_b64 v126, v[60:61], v[24:25] offset1:32
	ds_write2_b64 v127, v[46:47], v[14:15] offset0:64 offset1:96
	ds_write2_b64 v127, v[74:75], v[26:27] offset0:128 offset1:160
	ds_write2_b64 v127, v[62:63], v[16:17] offset0:192 offset1:224
	ds_write2_b64 v128, v[64:65], v[28:29] offset1:32
	s_waitcnt lgkmcnt(0)
	ds_read_b64 v[8:9], v125 offset:12288
	v_mul_f32_e32 v10, v18, v80
	v_exp_f32_e32 v10, v10
	v_mul_f32_e32 v19, v18, v101
	v_exp_f32_e32 v4, v4
	s_waitcnt lgkmcnt(0)
	v_mul_f32_e32 v12, v87, v9
	v_pk_fma_f32 v[12:13], v[86:87], v[8:9], v[12:13] op_sel_hi:[1,1,0]
	v_fma_f32 v17, -v10, v10, 1.0
	v_cvt_pk_bf16_f32 v11, v12, v8
	ds_read_b64 v[14:15], v125 offset:11776
	v_mov_b32_e32 v13, v158
	global_store_dword v[96:97], v11, off offset:2048
	v_exp_f32_e32 v6, v6
	s_mov_b32 s0, 0x13f08000
	s_waitcnt lgkmcnt(0)
	v_mul_f32_e32 v16, v158, v15
	v_pk_fma_f32 v[12:13], v[12:13], v[14:15], v[16:17] op_sel_hi:[1,1,0]
	v_pk_mul_f32 v[8:9], v[8:9], v[14:15]
	v_max_f32_e32 v13, 0, v17
	v_cvt_pk_bf16_f32 v11, v12, v8
	ds_read_b64 v[14:15], v125 offset:11264
	v_sqrt_f32_e32 v17, v13
	v_mov_b32_e32 v13, v157
	global_store_dword v[96:97], v11, off
	v_mul_f32_e32 v3, v49, v5
	s_waitcnt lgkmcnt(0)
	v_mul_f32_e32 v16, v157, v15
	v_pk_fma_f32 v[12:13], v[12:13], v[14:15], v[16:17] op_sel_hi:[1,1,0]
	v_pk_mul_f32 v[8:9], v[8:9], v[14:15]
	v_fma_f32 v5, -v4, v4, 1.0 clamp
	v_cvt_pk_bf16_f32 v13, v12, v8
	ds_read_b64 v[14:15], v125 offset:10752
	global_store_dword v[94:95], v13, off offset:2048
	v_mov_b32_e32 v13, v156
	v_fma_f32 v49, -v6, v6, 1.0
	v_mul_f32_e32 v11, v81, v17
	s_waitcnt lgkmcnt(0)
	v_mul_f32_e32 v16, v156, v15
	v_pk_fma_f32 v[12:13], v[12:13], v[14:15], v[16:17] op_sel_hi:[1,1,0]
	v_pk_mul_f32 v[8:9], v[8:9], v[14:15]
	v_mul_f32_e32 v16, v18, v84
	v_cvt_pk_bf16_f32 v13, v12, v8
	ds_read_b64 v[14:15], v125 offset:10240
	global_store_dword v[94:95], v13, off
	v_mov_b32_e32 v13, v155
	v_exp_f32_e32 v16, v16
	v_add_co_u32_e32 v66, vcc, s0, v88
	s_waitcnt lgkmcnt(0)
	v_mul_f32_e32 v20, v155, v15
	v_pk_fma_f32 v[12:13], v[12:13], v[14:15], v[20:21] op_sel_hi:[1,1,0]
	v_pk_mul_f32 v[8:9], v[8:9], v[14:15]
	v_fma_f32 v17, -v16, v16, 1.0 clamp
	v_cvt_pk_bf16_f32 v13, v12, v8
	ds_read_b64 v[14:15], v125 offset:9728
	global_store_dword v[92:93], v13, off offset:2048
	v_mov_b32_e32 v13, v154
	v_max_f32_e32 v7, 0, v49
	s_waitcnt lgkmcnt(0)
	v_mul_f32_e32 v20, v154, v15
	v_pk_fma_f32 v[12:13], v[12:13], v[14:15], v[20:21] op_sel_hi:[1,1,0]
	v_pk_mul_f32 v[8:9], v[8:9], v[14:15]
	v_exp_f32_e32 v20, v19
	v_cvt_pk_bf16_f32 v13, v12, v8
	ds_read_b64 v[14:15], v125 offset:9216
	global_store_dword v[92:93], v13, off
	v_mov_b32_e32 v13, v153
	v_fma_f32 v19, -v20, v20, 1.0 clamp
	s_waitcnt lgkmcnt(0)
	v_mul_f32_e32 v22, v153, v15
	v_pk_fma_f32 v[12:13], v[12:13], v[14:15], v[22:23] op_sel_hi:[1,1,0]
	v_pk_mul_f32 v[8:9], v[8:9], v[14:15]
	v_sqrt_f32_e32 v19, v19
	v_cvt_pk_bf16_f32 v13, v12, v8
	ds_read_b64 v[14:15], v125 offset:8704
	global_store_dword v[90:91], v13, off offset:2048
	v_mov_b32_e32 v13, v152
	v_mul_f32_e32 v21, v103, v19
	v_mul_f32_e32 v19, v18, v104
	s_waitcnt lgkmcnt(0)
	v_mul_f32_e32 v22, v152, v15
	v_pk_fma_f32 v[12:13], v[12:13], v[14:15], v[22:23] op_sel_hi:[1,1,0]
	v_pk_mul_f32 v[8:9], v[8:9], v[14:15]
	v_mul_f32_e32 v18, v18, v48
	v_cvt_pk_bf16_f32 v13, v12, v8
	ds_read_b64 v[14:15], v125 offset:8192
	global_store_dword v[90:91], v13, off
	v_mov_b32_e32 v13, v151
	v_exp_f32_e32 v18, v18
	s_waitcnt lgkmcnt(0)
	v_mul_f32_e32 v22, v151, v15
	v_pk_fma_f32 v[12:13], v[12:13], v[14:15], v[22:23] op_sel_hi:[1,1,0]
	v_pk_mul_f32 v[8:9], v[8:9], v[14:15]
	v_addc_co_u32_e32 v67, vcc, 0, v89, vcc
	v_cvt_pk_bf16_f32 v13, v12, v8
	ds_read_b64 v[14:15], v125 offset:7680
	global_store_dword v[72:73], v13, off offset:2048
	v_mov_b32_e32 v13, v150
	v_sqrt_f32_e32 v5, v5
	v_sqrt_f32_e32 v7, v7
	s_waitcnt lgkmcnt(0)
	v_mul_f32_e32 v22, v150, v15
	v_pk_fma_f32 v[12:13], v[12:13], v[14:15], v[22:23] op_sel_hi:[1,1,0]
	v_pk_mul_f32 v[8:9], v[8:9], v[14:15]
	v_fma_f32 v23, -v18, v18, 1.0 clamp
	v_cvt_pk_bf16_f32 v13, v12, v8
	ds_read_b64 v[14:15], v125 offset:7168
	global_store_dword v[72:73], v13, off
	v_mov_b32_e32 v13, v149
	v_exp_f32_e32 v22, v19
	s_waitcnt lgkmcnt(0)
; __device__ __forceinline__ unsigned cvt_pk_bf16(float lo, float hi) { unsigned r; asm volatile("v_cvt_pk_bf16_f32 %0, %1, %2" : "=v"(r) : "v"(lo), "v"(hi)); return r; }
; #define LAS __attribute__((address_space(3)))
; #define LDS_WAVE_SYNC() asm volatile("s_waitcnt lgkmcnt(0)" ::: "memory")
; template <int DIR, int MODE> ...
;     ...
;             for (int i = 0; i < 8; ++i) { const int tt = 8 * (i >> 2) + 4 * h + (i & 3);
;                 f32x2 v; v.x = accR[nt][8 * half + i]; v.y = accI[nt][8 * half + i];
;                 *(LAS f32x2*)(au + (tt * 64 + nt * 32 + r32) * 2) = v; }
;         LDS_WAVE_SYNC();
; #pragma unroll
;         for (int s = 0; s < 16; ++s) {
;             const int tt = DIR == 0 ? s : 15 - s, t = half * 16 + tt;
;             const f32x2 v = *(const LAS f32x2*)(au + (tt * 64 + lane) * 2);
;             hc = v.x * hc + v.y * xcr[t];
;             if (MODE == 0) { ap *= v.x;
;                 ((unsigned*)(a.ws + WS_HP))[((size_t)DIR * T + (size_t)b * SEQ + ch * 32 + t) * LW + c] = pg8::cvt_pk_bf16(hc, ap); }
	v_mul_f32_e32 v24, v149, v15
	v_pk_fma_f32 v[12:13], v[12:13], v[14:15], v[24:25] op_sel_hi:[1,1,0]
	v_pk_mul_f32 v[8:9], v[8:9], v[14:15]
	v_fma_f32 v19, -v22, v22, 1.0 clamp
	v_cvt_pk_bf16_f32 v13, v12, v8
	ds_read_b64 v[14:15], v125 offset:6656
	global_store_dword v[70:71], v13, off offset:2048
	v_mov_b32_e32 v13, v148
	v_sqrt_f32_e32 v17, v17
	s_waitcnt lgkmcnt(0)
	v_mul_f32_e32 v24, v148, v15
	v_pk_fma_f32 v[12:13], v[12:13], v[14:15], v[24:25] op_sel_hi:[1,1,0]
	v_pk_mul_f32 v[8:9], v[8:9], v[14:15]
	v_sqrt_f32_e32 v19, v19
	v_cvt_pk_bf16_f32 v13, v12, v8
	ds_read_b64 v[14:15], v125 offset:6144
	global_store_dword v[70:71], v13, off
	v_mov_b32_e32 v13, v147
	v_mul_f32_e32 v5, v77, v5
	v_mul_f32_e32 v7, v79, v7
	s_waitcnt lgkmcnt(0)
	v_mul_f32_e32 v24, v147, v15
	v_pk_fma_f32 v[12:13], v[12:13], v[14:15], v[24:25] op_sel_hi:[1,1,0]
	v_pk_mul_f32 v[8:9], v[8:9], v[14:15]
	v_mul_f32_e32 v17, v100, v17
	v_cvt_pk_bf16_f32 v13, v12, v8
	ds_read_b64 v[14:15], v125 offset:5632
	global_store_dword v[68:69], v13, off offset:2048
	v_mov_b32_e32 v13, v146
	s_mov_b32 s0, 0x13f07000
	s_waitcnt lgkmcnt(0)
	v_mul_f32_e32 v24, v146, v15
	v_pk_fma_f32 v[12:13], v[12:13], v[14:15], v[24:25] op_sel_hi:[1,1,0]
	v_pk_mul_f32 v[8:9], v[8:9], v[14:15]
	v_sqrt_f32_e32 v25, v23
	v_cvt_pk_bf16_f32 v13, v12, v8
	ds_read_b64 v[14:15], v125 offset:5120
	global_store_dword v[68:69], v13, off
	v_mov_b32_e32 v13, v145
	v_mul_f32_e32 v23, v105, v19
	v_mul_f32_e32 v19, v76, v25
	s_waitcnt lgkmcnt(0)
	v_mul_f32_e32 v24, v145, v15
	v_pk_fma_f32 v[12:13], v[12:13], v[14:15], v[24:25] op_sel_hi:[1,1,0]
	v_pk_mul_f32 v[8:9], v[8:9], v[14:15]
	s_nop 0
	v_cvt_pk_bf16_f32 v13, v12, v8
	ds_read_b64 v[14:15], v125 offset:4608
	global_store_dword v[66:67], v13, off offset:2048
	v_mov_b32_e32 v13, v144
	s_waitcnt lgkmcnt(0)
	v_mul_f32_e32 v24, v144, v15
	v_pk_fma_f32 v[12:13], v[12:13], v[14:15], v[24:25] op_sel_hi:[1,1,0]
	v_pk_mul_f32 v[8:9], v[8:9], v[14:15]
	s_nop 0
	v_cvt_pk_bf16_f32 v13, v12, v8
	global_store_dword v[66:67], v13, off
	s_waitcnt lgkmcnt(0)
	ds_write2_b64 v124, v[34:35], v[2:3] offset0:64 offset1:96
	ds_write2_b64 v124, v[36:37], v[4:5] offset0:128 offset1:160
	ds_write2_b64 v124, v[38:39], v[6:7] offset0:192 offset1:224
	ds_write2_b64 v126, v[40:41], v[10:11] offset1:32
	ds_write2_b64 v127, v[50:51], v[16:17] offset0:64 offset1:96
	ds_write2_b64 v127, v[52:53], v[20:21] offset0:128 offset1:160
	ds_write2_b64 v127, v[54:55], v[22:23] offset0:192 offset1:224
	ds_write2_b64 v128, v[56:57], v[18:19] offset1:32
	s_waitcnt lgkmcnt(0)
	ds_read_b64 v[2:3], v125 offset:12288
	v_mov_b32_e32 v13, v143
	s_waitcnt lgkmcnt(0)
	v_mul_f32_e32 v4, v143, v3
	v_pk_fma_f32 v[4:5], v[12:13], v[2:3], v[4:5] op_sel_hi:[1,1,0]
	v_pk_mul_f32 v[2:3], v[8:9], v[2:3]
	v_add_co_u32_e32 v8, vcc, s0, v88
	v_cvt_pk_bf16_f32 v5, v4, v2
	ds_read_b64 v[6:7], v125 offset:11776
	s_nop 0
	v_addc_co_u32_e32 v9, vcc, 0, v89, vcc
	global_store_dword v[8:9], v5, off offset:2048
	v_mov_b32_e32 v5, v142
	s_waitcnt lgkmcnt(0)
	v_mul_f32_e32 v10, v142, v7
	v_pk_fma_f32 v[4:5], v[4:5], v[6:7], v[10:11] op_sel_hi:[1,1,0]
	v_pk_mul_f32 v[2:3], v[2:3], v[6:7]
	s_mov_b32 s0, 0x13f06000
	v_cvt_pk_bf16_f32 v5, v4, v2
	ds_read_b64 v[6:7], v125 offset:11264
	global_store_dword v[8:9], v5, off
	v_mov_b32_e32 v5, v141
	v_lshl_add_u64 v[12:13], s[40:41], 0, v[82:83]
	s_waitcnt lgkmcnt(0)
	v_mul_f32_e32 v8, v141, v7
	v_pk_fma_f32 v[4:5], v[4:5], v[6:7], v[8:9] op_sel_hi:[1,1,0]
	v_pk_mul_f32 v[2:3], v[2:3], v[6:7]
	v_add_co_u32_e32 v8, vcc, s0, v88
	v_cvt_pk_bf16_f32 v5, v4, v2
	ds_read_b64 v[6:7], v125 offset:10752
	s_nop 0
	v_addc_co_u32_e32 v9, vcc, 0, v89, vcc
	global_store_dword v[8:9], v5, off offset:2048
	v_mov_b32_e32 v5, v140
	s_waitcnt lgkmcnt(0)
	v_mul_f32_e32 v10, v140, v7
	v_pk_fma_f32 v[4:5], v[4:5], v[6:7], v[10:11] op_sel_hi:[1,1,0]
	v_pk_mul_f32 v[2:3], v[2:3], v[6:7]
	s_mov_b32 s0, 0x13f05000
	v_cvt_pk_bf16_f32 v5, v4, v2
	ds_read_b64 v[6:7], v125 offset:10240
	global_store_dword v[8:9], v5, off
	v_mov_b32_e32 v5, v139
	s_waitcnt lgkmcnt(0)
; __device__ __forceinline__ unsigned cvt_pk_bf16(float lo, float hi) { unsigned r; asm volatile("v_cvt_pk_bf16_f32 %0, %1, %2" : "=v"(r) : "v"(lo), "v"(hi)); return r; }
; #define LAS __attribute__((address_space(3)))
; #define LDS_WAVE_SYNC() asm volatile("s_waitcnt lgkmcnt(0)" ::: "memory")
; template <int DIR, int MODE> ...
;     ...
; #pragma unroll
;         for (int s = 0; s < 16; ++s) {
;             const int tt = DIR == 0 ? s : 15 - s, t = half * 16 + tt;
;             const f32x2 v = *(const LAS f32x2*)(au + (tt * 64 + lane) * 2);
;             hc = v.x * hc + v.y * xcr[t];
;             if (MODE == 0) { ap *= v.x;
;                 ((unsigned*)(a.ws + WS_HP))[((size_t)DIR * T + (size_t)b * SEQ + ch * 32 + t) * LW + c] = pg8::cvt_pk_bf16(hc, ap); }
;             if (MODE == 1) { if (DIR == 0) hf[t] = hc; else hf[t] = gl[t] * (hf[t] + hc); }
;         }
;         LDS_WAVE_SYNC();
;     }
;     if (MODE == 0) { f32x2 v; v.x = ap; v.y = hc; ((f32x2*)(a.ws + WS_TOT))[(size_t)((b * NCH + ch) * 2 + DIR) * LW + c] = v; }
	v_mul_f32_e32 v8, v139, v7
	v_pk_fma_f32 v[4:5], v[4:5], v[6:7], v[8:9] op_sel_hi:[1,1,0]
	v_pk_mul_f32 v[2:3], v[2:3], v[6:7]
	v_add_co_u32_e32 v8, vcc, s0, v88
	v_cvt_pk_bf16_f32 v5, v4, v2
	ds_read_b64 v[6:7], v125 offset:9728
	s_nop 0
	v_addc_co_u32_e32 v9, vcc, 0, v89, vcc
	global_store_dword v[8:9], v5, off offset:2048
	v_mov_b32_e32 v5, v138
	s_waitcnt lgkmcnt(0)
	v_mul_f32_e32 v10, v138, v7
	v_pk_fma_f32 v[4:5], v[4:5], v[6:7], v[10:11] op_sel_hi:[1,1,0]
	v_pk_mul_f32 v[2:3], v[2:3], v[6:7]
	s_mov_b32 s0, 0x13f04000
	v_cvt_pk_bf16_f32 v5, v4, v2
	ds_read_b64 v[6:7], v125 offset:9216
	global_store_dword v[8:9], v5, off
	v_mov_b32_e32 v5, v137
	s_waitcnt lgkmcnt(0)
	v_mul_f32_e32 v8, v137, v7
	v_pk_fma_f32 v[4:5], v[4:5], v[6:7], v[8:9] op_sel_hi:[1,1,0]
	v_pk_mul_f32 v[2:3], v[2:3], v[6:7]
	v_add_co_u32_e32 v8, vcc, s0, v88
	v_cvt_pk_bf16_f32 v5, v4, v2
	ds_read_b64 v[6:7], v125 offset:8704
	s_nop 0
	v_addc_co_u32_e32 v9, vcc, 0, v89, vcc
	global_store_dword v[8:9], v5, off offset:2048
	v_mov_b32_e32 v5, v136
	s_waitcnt lgkmcnt(0)
	v_mul_f32_e32 v10, v136, v7
	v_pk_fma_f32 v[4:5], v[4:5], v[6:7], v[10:11] op_sel_hi:[1,1,0]
	v_pk_mul_f32 v[2:3], v[2:3], v[6:7]
	s_mov_b32 s0, 0x13f03000
	v_cvt_pk_bf16_f32 v5, v4, v2
	ds_read_b64 v[6:7], v125 offset:8192
	global_store_dword v[8:9], v5, off
	v_mov_b32_e32 v5, v135
	s_waitcnt lgkmcnt(0)
	v_mul_f32_e32 v8, v135, v7
	v_pk_fma_f32 v[4:5], v[4:5], v[6:7], v[8:9] op_sel_hi:[1,1,0]
	v_pk_mul_f32 v[2:3], v[2:3], v[6:7]
	v_add_co_u32_e32 v8, vcc, s0, v88
	v_cvt_pk_bf16_f32 v5, v4, v2
	ds_read_b64 v[6:7], v125 offset:7680
	s_nop 0
	v_addc_co_u32_e32 v9, vcc, 0, v89, vcc
	global_store_dword v[8:9], v5, off offset:2048
	v_mov_b32_e32 v5, v134
	s_waitcnt lgkmcnt(0)
	v_mul_f32_e32 v10, v134, v7
	v_pk_fma_f32 v[4:5], v[4:5], v[6:7], v[10:11] op_sel_hi:[1,1,0]
	v_pk_mul_f32 v[2:3], v[2:3], v[6:7]
	s_mov_b32 s0, 0x13f02000
	v_cvt_pk_bf16_f32 v5, v4, v2
	ds_read_b64 v[6:7], v125 offset:7168
	global_store_dword v[8:9], v5, off
	v_mov_b32_e32 v5, v133
	s_waitcnt lgkmcnt(0)
	v_mul_f32_e32 v8, v133, v7
	v_pk_fma_f32 v[4:5], v[4:5], v[6:7], v[8:9] op_sel_hi:[1,1,0]
	v_pk_mul_f32 v[2:3], v[2:3], v[6:7]
	v_add_co_u32_e32 v8, vcc, s0, v88
	v_cvt_pk_bf16_f32 v5, v4, v2
	ds_read_b64 v[6:7], v125 offset:6656
	s_nop 0
	v_addc_co_u32_e32 v9, vcc, 0, v89, vcc
	global_store_dword v[8:9], v5, off offset:2048
	v_mov_b32_e32 v5, v132
	s_waitcnt lgkmcnt(0)
	v_mul_f32_e32 v10, v132, v7
	v_pk_fma_f32 v[4:5], v[4:5], v[6:7], v[10:11] op_sel_hi:[1,1,0]
	v_pk_mul_f32 v[2:3], v[2:3], v[6:7]
	s_mov_b32 s0, 0x13f01000
	v_cvt_pk_bf16_f32 v5, v4, v2
	ds_read_b64 v[6:7], v125 offset:6144
	global_store_dword v[8:9], v5, off
	v_mov_b32_e32 v5, v131
	v_add_co_u32_e32 v10, vcc, s0, v88
	s_waitcnt lgkmcnt(0)
	v_mul_f32_e32 v8, v131, v7
	v_pk_fma_f32 v[4:5], v[4:5], v[6:7], v[8:9] op_sel_hi:[1,1,0]
	v_pk_mul_f32 v[2:3], v[2:3], v[6:7]
	v_addc_co_u32_e32 v11, vcc, 0, v89, vcc
	v_cvt_pk_bf16_f32 v5, v4, v2
	ds_read_b64 v[6:7], v125 offset:5632
	global_store_dword v[10:11], v5, off offset:2048
	v_mov_b32_e32 v5, v130
	s_mov_b32 s0, 0x13f00000
	v_add_co_u32_e32 v8, vcc, s0, v88
	s_waitcnt lgkmcnt(0)
	v_mul_f32_e32 v14, v130, v7
	v_pk_fma_f32 v[4:5], v[4:5], v[6:7], v[14:15] op_sel_hi:[1,1,0]
	v_pk_mul_f32 v[2:3], v[2:3], v[6:7]
	v_addc_co_u32_e32 v9, vcc, 0, v89, vcc
	v_cvt_pk_bf16_f32 v5, v4, v2
	ds_read_b64 v[6:7], v125 offset:5120
	global_store_dword v[10:11], v5, off
	v_mov_b32_e32 v5, v0
	v_add_co_u32_e32 v12, vcc, 0x11901000, v12
	s_waitcnt lgkmcnt(0)
	v_mul_f32_e32 v0, v0, v7
	v_pk_fma_f32 v[4:5], v[4:5], v[6:7], v[0:1] op_sel_hi:[1,1,0]
	v_pk_mul_f32 v[2:3], v[2:3], v[6:7]
	v_mov_b32_e32 v5, v85
	v_cvt_pk_bf16_f32 v0, v4, v2
	ds_read_b64 v[6:7], v125 offset:4608
	global_store_dword v[8:9], v0, off offset:2048
	v_addc_co_u32_e32 v13, vcc, 0, v13, vcc
	s_mov_b64 s[0:1], 0
	s_waitcnt lgkmcnt(0)
	v_mul_f32_e32 v0, v85, v7
	v_pk_fma_f32 v[4:5], v[4:5], v[6:7], v[0:1] op_sel_hi:[1,1,0]
	v_pk_mul_f32 v[2:3], v[2:3], v[6:7]
	s_nop 0
	v_cvt_pk_bf16_f32 v0, v4, v2
	global_store_dword v[8:9], v0, off
	s_waitcnt lgkmcnt(0)
	v_mov_b32_e32 v3, v4
	global_store_dwordx2 v[12:13], v[2:3], off
